# half-tile (MB=1) gate and w_out K-loops: waves 4-7 staggered half a K-tile behind, same scheme as the full-tile loops
# baseline (speedup 1.0000x reference)
; DI void wait_vm0() { asm volatile("s_waitcnt vmcnt(0)" ::: "memory"); }
; DI int otid() { int t = threadIdx.x; asm volatile("" : "+v"(t)); return t; }
; template <int MB, bool SWAP>
; DI void gemm_kloop(f32x16 (&acc)[MB][2], const h16* __restrict__ A, int lda, const h16* __restrict__ B, int ldb, int K, char* lds) {
;   constexpr int A_BYTES = 64 * MB * 128, B_BYTES = 256 * 128, STAGE = A_BYTES + B_BYTES;
;   static_assert(3 * STAGE <= LDS_BYTES, "ring does not fit");
;   const int tid = otid(), w = tid >> 6, lane = tid & 63;
;   const int wr = w >> 2, wc = w & 3;
;   const int lrow = w * 8 + (lane >> 3), pch = lane & 7;
;   const int gch = pch ^ ((lrow >> 1) & 7);
;   const unsigned voa = (unsigned)(lrow * lda + gch * 8) * 2u, vob = (unsigned)(lrow * ldb + gch * 8) * 2u;
;   const int lofs = lrow * 128 + pch * 16;
;   const int r32 = lane & 31, hh = lane >> 5, sw = (r32 >> 1) & 7;
;   const int a_rd = (wr * 32 * MB + r32) * 128;
;   const int b_rd = A_BYTES + (wc * 64 + r32) * 128;
;   const int nk = K >> 6;
;   constexpr int NP = MB + 4;
;   auto piece = [&](int p, int kt, int buf) {
;     char* s = lds + buf * STAGE;
;     if (p < MB) __builtin_amdgcn_global_load_lds((const unsigned*)((const char*)(A + (size_t)p * 64 * lda + kt * 64) + voa), (unsigned*)(s + p * 8192 + lofs), 16, 0, 0);
;     else __builtin_amdgcn_global_load_lds((const unsigned*)((const char*)(B + (size_t)(p - MB) * 64 * ldb + kt * 64) + vob), (unsigned*)(s + A_BYTES + (p - MB) * 8192 + lofs), 16, 0, 0);
;   };
;   wait_vm0();
; #pragma unroll
;   for (int p = 0; p < NP; ++p) piece(p, 0, 0);
; #pragma unroll
;   for (int p = 0; p < NP; ++p) piece(p, 1, 1);
;   int cur = 0;
;   for (int kt = 0; kt < nk; ++kt) {
;     if (kt + 1 < nk) { if (MB == 2) asm volatile("s_waitcnt vmcnt(6)" ::: "memory"); else asm volatile("s_waitcnt vmcnt(5)" ::: "memory"); }
;     else wait_vm0();
;     __syncthreads();
; template <int MB>
; DI void merge_tile(const Params& P, int layer, size_t row0, int nt, char* smem) {
;     ...
;     zero_acc<MB>(pa2);
;     gemm_kloop<MB, true>(pa2, hb + row0 * LDH, LDH, winT + (size_t)(G_OFF + n * 1024 + nt * 256) * LDH, LDH, D, smem);
.LBB0_62:
	v_mov_b32_e32 v6, v208
	s_lshl_b32 s51, s97, 10
	v_ashrrev_i32_e32 v7, 3, v6
	v_bfe_u32 v8, v6, 3, 3
	v_and_or_b32 v0, v7, -8, v8
	v_lshrrev_b32_e32 v1, 1, v0
	v_xor_b32_e32 v1, v1, v6
	v_lshlrev_b32_e32 v1, 3, v1
	v_mul_lo_u32 v2, v0, s6
	v_and_b32_e32 v9, 56, v1
	v_or_b32_e32 v1, v9, v2
	v_lshlrev_b32_e32 v128, 1, v1
	v_lshlrev_b32_e32 v1, 4, v6
	v_and_b32_e32 v1, 0x70, v1
	s_add_i32 s0, s86, s51
	v_lshl_or_b32 v10, v0, 7, v1
	s_mul_i32 s84, s0, 0x440
	v_add_u32_e32 v42, 0, v10
	s_lshl_b64 s[0:1], s[84:85], 1
	v_readfirstlane_b32 s2, v42
	v_add_u32_e32 v4, 0x2000, v42
	s_add_u32 s0, s70, s0
	s_waitcnt vmcnt(0)
	s_mov_b32 m0, s2
	v_readfirstlane_b32 s2, v4
	s_addc_u32 s1, s71, s1
	global_load_lds_dwordx4 v128, s[38:39]
	s_mov_b32 m0, s2
	v_lshl_add_u64 v[0:1], s[0:1], 0, v[128:129]
	global_load_lds_dwordx4 v128, s[0:1]
	s_mov_b64 s[0:1], 0x22000
	v_add_u32_e32 v11, 0x4000, v42
	v_lshl_add_u64 v[4:5], v[0:1], 0, s[0:1]
	v_readfirstlane_b32 s0, v11
	s_mov_b32 m0, s0
	s_mov_b64 s[0:1], 0x44000
	v_add_u32_e32 v11, 0x6000, v42
	global_load_lds_dwordx4 v[4:5], off
	v_lshl_add_u64 v[4:5], v[0:1], 0, s[0:1]
	v_readfirstlane_b32 s0, v11
	s_mov_b32 m0, s0
	s_mov_b64 s[0:1], 0x66000
	v_add_u32_e32 v11, 0x8000, v42
	global_load_lds_dwordx4 v[4:5], off
	v_lshl_add_u64 v[4:5], v[0:1], 0, s[0:1]
	v_readfirstlane_b32 s0, v11
	s_mov_b32 m0, s0
	v_lshl_add_u64 v[2:3], s[38:39], 0, v[128:129]
	global_load_lds_dwordx4 v[4:5], off
	v_add_u32_e32 v4, 0xa000, v42
	v_lshl_add_u64 v[2:3], v[2:3], 0, s[22:23]
	v_readfirstlane_b32 s0, v4
	v_add_u32_e32 v4, 0xc000, v42
	s_mov_b32 m0, s0
	v_readfirstlane_b32 s0, v4
	global_load_lds_dwordx4 v[2:3], off
	v_lshl_add_u64 v[2:3], v[0:1], 0, s[22:23]
	s_mov_b32 m0, s0
	s_mov_b64 s[0:1], 0x22080
	v_add_u32_e32 v4, 0xe000, v42
	global_load_lds_dwordx4 v[2:3], off
	v_lshl_add_u64 v[2:3], v[0:1], 0, s[0:1]
	v_readfirstlane_b32 s0, v4
	s_mov_b32 m0, s0
	s_mov_b64 s[0:1], 0x44080
	v_add_u32_e32 v4, s8, v10
	global_load_lds_dwordx4 v[2:3], off
	v_lshl_add_u64 v[2:3], v[0:1], 0, s[0:1]
	v_readfirstlane_b32 s0, v4
	s_mov_b32 m0, s0
	s_mov_b64 s[0:1], 0x66080
	global_load_lds_dwordx4 v[2:3], off
	v_add_u32_e32 v2, s9, v10
	v_lshl_add_u64 v[0:1], v[0:1], 0, s[0:1]
	v_readfirstlane_b32 s0, v2
	s_mov_b32 m0, s0
	v_lshlrev_b32_e32 v2, 7, v6
	global_load_lds_dwordx4 v[0:1], off
	v_and_b32_e32 v0, 31, v6
	v_lshrrev_b32_e32 v1, 1, v6
	v_and_or_b32 v0, v7, s16, v0
	v_and_b32_e32 v39, 0x6f80, v2
	v_bfe_u32 v2, v6, 5, 1
	v_lshlrev_b32_e32 v41, 7, v0
	v_bfe_u32 v0, v6, 1, 3
	v_bitop3_b32 v1, v2, v1, 7 bitop3:0x78
	v_lshlrev_b32_e32 v40, 4, v1
	v_bitop3_b32 v1, v2, v0, 2 bitop3:0x36
	v_lshlrev_b32_e32 v38, 4, v1
	v_bitop3_b32 v1, v2, v0, 4 bitop3:0x36
	v_bitop3_b32 v0, v2, v0, 6 bitop3:0x36
	v_lshlrev_b32_e32 v36, 4, v0
	v_lshrrev_b32_e32 v0, 3, v7
	v_mul_lo_u32 v0, v0, s11
	v_mad_u32_u24 v0, v8, s6, v0
	v_or_b32_e32 v0, v0, v9
	v_lshlrev_b32_e32 v128, 1, v0
	v_lshlrev_b32_e32 v37, 4, v1
	v_lshl_add_u64 v[32:33], s[40:41], 0, v[128:129]
	v_lshl_add_u64 v[34:35], s[42:43], 0, v[128:129]
	s_mov_b64 s[2:3], 0
	s_mov_b32 s0, 0
	v_mov_b32_e32 v16, 0
	v_mov_b32_e32 v17, v108
	v_mov_b32_e32 v18, v108
	v_mov_b32_e32 v19, v108
	v_mov_b32_e32 v20, v108
	v_mov_b32_e32 v21, v108
	v_mov_b32_e32 v22, v108
	v_mov_b32_e32 v23, v108
	v_mov_b32_e32 v24, v108
	v_mov_b32_e32 v25, v108
	v_mov_b32_e32 v26, v108
	v_mov_b32_e32 v27, v108
	v_mov_b32_e32 v28, v108
	v_mov_b32_e32 v29, v108
	v_mov_b32_e32 v30, v108
	v_mov_b32_e32 v31, v108
	v_mov_b32_e32 v0, 0
	v_mov_b32_e32 v1, v108
	v_mov_b32_e32 v2, v108
	v_mov_b32_e32 v3, v108
	v_mov_b32_e32 v4, v108
	v_mov_b32_e32 v5, v108
	v_mov_b32_e32 v6, v108
	v_mov_b32_e32 v7, v108
	v_mov_b32_e32 v8, v108
	v_mov_b32_e32 v9, v108
	v_mov_b32_e32 v10, v108
	v_mov_b32_e32 v11, v108
	v_mov_b32_e32 v12, v108
	v_mov_b32_e32 v13, v108
	v_mov_b32_e32 v14, v108
	v_mov_b32_e32 v15, v108
	s_mov_b64 s[52:53], 0xb6c180
	s_mov_b64 s[54:55], 0xb4a180
	v_readfirstlane_b32 s1, v208
	s_nop 0
	s_lshr_b32 s1, s1, 8
	s_cmp_lg_u32 s1, 0
	s_cbranch_scc1 .Lst1_63_top
.LBB0_63:
	s_mul_i32 s1, s0, 0xa000
	s_add_i32 s24, s1, 0
	s_add_i32 s1, s1, 0xffff6000
	s_cmp_lg_u32 s0, 0
	s_cselect_b32 s1, s1, 0x14000
	v_add_u32_e32 v110, s1, v42
	v_add_u32_e32 v43, s24, v41
	v_add_u32_e32 v109, s24, v39
	v_add_u32_e32 v111, 0x2000, v110
	v_lshl_add_u64 v[100:101], v[32:33], 0, s[2:3]
	v_readfirstlane_b32 s1, v110
	v_add_u32_e32 v76, v109, v40
	v_lshl_add_u64 v[96:97], v[34:35], 0, s[2:3]
	v_add_u32_e32 v80, v43, v40
	v_add_u32_e32 v84, v43, v38
	v_add_u32_e32 v92, v109, v38
	v_lshl_add_u64 v[102:103], v[100:101], 0, s[90:91]
	s_mov_b32 m0, s1
	v_readfirstlane_b32 s1, v111
	s_waitcnt vmcnt(5)
	s_waitcnt lgkmcnt(0)
	s_barrier
; DI void wait_vm0() { asm volatile("s_waitcnt vmcnt(0)" ::: "memory"); }
; template <int MB, bool SWAP>
; DI void gemm_kloop(f32x16 (&acc)[MB][2], const h16* __restrict__ A, int lda, const h16* __restrict__ B, int ldb, int K, char* lds) {
;     ...
;   for (int kt = 0; kt < nk; ++kt) {
;     if (kt + 1 < nk) { if (MB == 2) asm volatile("s_waitcnt vmcnt(6)" ::: "memory"); else asm volatile("s_waitcnt vmcnt(5)" ::: "memory"); }
;     else wait_vm0();
;     __syncthreads();
;     const char* s = lds + cur * STAGE;
;     const int nbuf = cur == 0 ? 2 : cur - 1;
;     const bool more = kt + 2 < nk;
;     half8 af[2][MB], bf[2][2];
; #pragma unroll
;     for (int mb = 0; mb < MB; ++mb) af[0][mb] = *(const half8*)(s + a_rd + mb * 4096 + (((0 + hh) ^ sw) * 16));
; #pragma unroll
;     for (int nb = 0; nb < 2; ++nb) bf[0][nb] = *(const half8*)(s + b_rd + nb * 4096 + (((0 + hh) ^ sw) * 16));
; #pragma unroll
;     for (int ks = 0; ks < 4; ++ks) {
;       if (ks < 3) {
; #pragma unroll
;         for (int mb = 0; mb < MB; ++mb) af[(ks + 1) & 1][mb] = *(const half8*)(s + a_rd + mb * 4096 + (((2 * (ks + 1) + hh) ^ sw) * 16));
; #pragma unroll
;         for (int nb = 0; nb < 2; ++nb) bf[(ks + 1) & 1][nb] = *(const half8*)(s + b_rd + nb * 4096 + (((2 * (ks + 1) + hh) ^ sw) * 16));
;       }
;       if (more) {
;         if (2 * ks < NP) piece(2 * ks, kt + 2, nbuf);
;         if (2 * ks + 1 < NP) piece(2 * ks + 1, kt + 2, nbuf);
;       }
;       __builtin_amdgcn_sched_barrier(0);
;       __builtin_amdgcn_s_setprio(1);
; #pragma unroll
;       for (int mb = 0; mb < MB; ++mb)
; #pragma unroll
;         for (int nb = 0; nb < 2; ++nb)
;           acc[mb][nb] = SWAP ? __builtin_amdgcn_mfma_f32_32x32x16_f16(bf[ks & 1][nb], af[ks & 1][mb], acc[mb][nb], 0, 0, 0)
;                              : __builtin_amdgcn_mfma_f32_32x32x16_f16(af[ks & 1][mb], bf[ks & 1][nb], acc[mb][nb], 0, 0, 0);
;       __builtin_amdgcn_s_setprio(0);
;       __builtin_amdgcn_sched_barrier(0);
;     }
	ds_read_b128 v[72:75], v76 offset:8192
	ds_read_b128 v[76:79], v76 offset:12288
	v_lshl_add_u64 v[98:99], v[96:97], 0, s[72:73]
	ds_read_b128 v[80:83], v80
	ds_read_b128 v[84:87], v84
	ds_read_b128 v[88:91], v92 offset:8192
	ds_read_b128 v[92:95], v92 offset:12288
	global_load_lds_dwordx4 v[102:103], off
	s_mov_b32 m0, s1
	s_nop 0
	global_load_lds_dwordx4 v[98:99], off
	s_setprio 1
	s_waitcnt lgkmcnt(0)
	v_mfma_f32_32x32x16_f16 v[16:31], v[72:75], v[80:83], v[16:31]
	v_mfma_f32_32x32x16_f16 v[0:15], v[76:79], v[80:83], v[0:15]
	s_setprio 0
	v_add_u32_e32 v112, 0x4000, v110
	v_add_u32_e32 v111, 0x6000, v110
	v_readfirstlane_b32 s1, v112
	v_add_u32_e32 v72, v43, v37
	v_add_u32_e32 v80, v109, v37
	v_lshl_add_u64 v[102:103], v[96:97], 0, s[88:89]
	s_mov_b32 m0, s1
	v_readfirstlane_b32 s1, v111
	ds_read_b128 v[72:75], v72
	ds_read_b128 v[76:79], v80 offset:8192
	ds_read_b128 v[80:83], v80 offset:12288
	v_lshl_add_u64 v[98:99], v[96:97], 0, s[68:69]
	global_load_lds_dwordx4 v[102:103], off
	s_mov_b32 m0, s1
	s_nop 0
	global_load_lds_dwordx4 v[98:99], off
	s_setprio 1
	v_mfma_f32_32x32x16_f16 v[16:31], v[88:91], v[84:87], v[16:31]
	v_mfma_f32_32x32x16_f16 v[0:15], v[92:95], v[84:87], v[0:15]
	s_setprio 0
	v_add_u32_e32 v43, v43, v36
	v_add_u32_e32 v92, v109, v36
	ds_read_b128 v[84:87], v43
	ds_read_b128 v[88:91], v92 offset:8192
	ds_read_b128 v[92:95], v92 offset:12288
	v_add_u32_e32 v43, 0x8000, v110
	v_lshl_add_u64 v[98:99], v[96:97], 0, s[34:35]
	v_readfirstlane_b32 s1, v43
	s_mov_b32 m0, s1
	s_nop 0
	global_load_lds_dwordx4 v[98:99], off
	s_setprio 1
	s_waitcnt lgkmcnt(0)
	v_mfma_f32_32x32x16_f16 v[16:31], v[76:79], v[72:75], v[16:31]
	v_mfma_f32_32x32x16_f16 v[0:15], v[80:83], v[72:75], v[0:15]
	s_setprio 0
	s_setprio 1
	v_mfma_f32_32x32x16_f16 v[16:31], v[88:91], v[84:87], v[16:31]
	v_mfma_f32_32x32x16_f16 v[0:15], v[92:95], v[84:87], v[0:15]
	s_setprio 0
	s_add_i32 s1, s0, 1
	s_cmp_lg_u32 s0, 2
	s_cselect_b32 s0, s1, 0
	s_mul_i32 s1, s0, 0xa000
	s_add_i32 s24, s1, 0
	s_add_i32 s1, s1, 0xffff6000
	s_cmp_lg_u32 s0, 0
	s_cselect_b32 s1, s1, 0x14000
	v_add_u32_e32 v103, s1, v42
	v_add_u32_e32 v43, s24, v41
	v_add_u32_e32 v102, s24, v39
	v_add_u32_e32 v109, 0x2000, v103
	v_readfirstlane_b32 s1, v103
	v_add_u32_e32 v76, v102, v40
	v_add_u32_e32 v80, v43, v40
	v_add_u32_e32 v84, v43, v38
	v_add_u32_e32 v92, v102, v38
	v_lshl_add_u64 v[100:101], v[100:101], 0, vcc
	s_mov_b32 m0, s1
	v_readfirstlane_b32 s1, v109
	s_waitcnt vmcnt(5)
	s_waitcnt lgkmcnt(0)
	s_barrier
	ds_read_b128 v[72:75], v76 offset:8192
	ds_read_b128 v[76:79], v76 offset:12288
	v_lshl_add_u64 v[98:99], v[96:97], 0, s[44:45]
	ds_read_b128 v[80:83], v80
	ds_read_b128 v[84:87], v84
	ds_read_b128 v[88:91], v92 offset:8192
	ds_read_b128 v[92:95], v92 offset:12288
	global_load_lds_dwordx4 v[100:101], off
	s_mov_b32 m0, s1
	s_nop 0
	global_load_lds_dwordx4 v[98:99], off
	s_setprio 1
	s_waitcnt lgkmcnt(0)
	v_mfma_f32_32x32x16_f16 v[16:31], v[72:75], v[80:83], v[16:31]
	v_mfma_f32_32x32x16_f16 v[0:15], v[76:79], v[80:83], v[0:15]
	s_setprio 0
	v_add_u32_e32 v110, 0x4000, v103
	v_add_u32_e32 v109, 0x6000, v103
	v_readfirstlane_b32 s1, v110
	v_add_u32_e32 v72, v43, v37
	v_add_u32_e32 v80, v102, v37
	v_lshl_add_u64 v[100:101], v[96:97], 0, s[54:55]
	s_mov_b32 m0, s1
	v_readfirstlane_b32 s1, v109
	ds_read_b128 v[72:75], v72
	ds_read_b128 v[76:79], v80 offset:8192
	ds_read_b128 v[80:83], v80 offset:12288
	v_lshl_add_u64 v[98:99], v[96:97], 0, s[52:53]
	global_load_lds_dwordx4 v[100:101], off
	s_mov_b32 m0, s1
	s_nop 0
	global_load_lds_dwordx4 v[98:99], off
	s_setprio 1
	v_mfma_f32_32x32x16_f16 v[16:31], v[88:91], v[84:87], v[16:31]
	v_mfma_f32_32x32x16_f16 v[0:15], v[92:95], v[84:87], v[0:15]
	s_setprio 0
	v_add_u32_e32 v43, v43, v36
	v_add_u32_e32 v92, v102, v36
	ds_read_b128 v[84:87], v43
	ds_read_b128 v[88:91], v92 offset:8192
	ds_read_b128 v[92:95], v92 offset:12288
	v_add_u32_e32 v43, 0x8000, v103
	v_lshl_add_u64 v[96:97], v[96:97], 0, s[94:95]
	v_readfirstlane_b32 s1, v43
	s_mov_b32 m0, s1
	s_nop 0
	global_load_lds_dwordx4 v[96:97], off
	s_setprio 1
	s_waitcnt lgkmcnt(0)
	v_mfma_f32_32x32x16_f16 v[16:31], v[76:79], v[72:75], v[16:31]
	v_mfma_f32_32x32x16_f16 v[0:15], v[80:83], v[72:75], v[0:15]
	s_setprio 0
	s_setprio 1
	v_mfma_f32_32x32x16_f16 v[16:31], v[88:91], v[84:87], v[16:31]
	v_mfma_f32_32x32x16_f16 v[0:15], v[92:95], v[84:87], v[0:15]
	s_setprio 0
	s_add_i32 s1, s0, 1
	s_cmp_lg_u32 s0, 2
	s_cselect_b32 s0, s1, 0
	s_add_u32 s2, s2, 0x100
	s_addc_u32 s3, s3, 0
	s_cmpk_eq_i32 s2, 0x700
	s_cbranch_scc0 .LBB0_63
	s_branch .Lst1_63_join
.Lst1_63_top:
	s_mul_i32 s1, s0, 0xa000
	s_add_i32 s24, s1, 0
	s_add_i32 s1, s1, 0xffff6000
	s_cmp_lg_u32 s0, 0
	s_cselect_b32 s1, s1, 0x14000
	v_add_u32_e32 v110, s1, v42
	v_add_u32_e32 v43, s24, v41
	v_add_u32_e32 v109, s24, v39
	v_add_u32_e32 v111, 0x2000, v110
	v_lshl_add_u64 v[100:101], v[32:33], 0, s[2:3]
	v_readfirstlane_b32 s1, v110
	v_lshl_add_u64 v[96:97], v[34:35], 0, s[2:3]
	v_lshl_add_u64 v[102:103], v[100:101], 0, s[90:91]
	s_mov_b32 m0, s1
	v_readfirstlane_b32 s1, v111
	s_waitcnt vmcnt(5)
	s_waitcnt lgkmcnt(0)
	s_barrier
	s_cmp_eq_u32 s2, 0
	s_cbranch_scc1 .Lst1_63_skip
	s_setprio 1
	v_mfma_f32_32x32x16_f16 v[16:31], v[76:79], v[72:75], v[16:31]
	v_mfma_f32_32x32x16_f16 v[0:15], v[80:83], v[72:75], v[0:15]
	v_mfma_f32_32x32x16_f16 v[16:31], v[88:91], v[84:87], v[16:31]
	v_mfma_f32_32x32x16_f16 v[0:15], v[92:95], v[84:87], v[0:15]
	s_setprio 0
; DI void wait_vm0() { asm volatile("s_waitcnt vmcnt(0)" ::: "memory"); }
; template <int MB, bool SWAP>
; DI void gemm_kloop(f32x16 (&acc)[MB][2], const h16* __restrict__ A, int lda, const h16* __restrict__ B, int ldb, int K, char* lds) {
;     ...
;   for (int kt = 0; kt < nk; ++kt) {
;     if (kt + 1 < nk) { if (MB == 2) asm volatile("s_waitcnt vmcnt(6)" ::: "memory"); else asm volatile("s_waitcnt vmcnt(5)" ::: "memory"); }
;     else wait_vm0();
;     __syncthreads();
;     const char* s = lds + cur * STAGE;
;     const int nbuf = cur == 0 ? 2 : cur - 1;
;     const bool more = kt + 2 < nk;
;     half8 af[2][MB], bf[2][2];
; #pragma unroll
;     for (int mb = 0; mb < MB; ++mb) af[0][mb] = *(const half8*)(s + a_rd + mb * 4096 + (((0 + hh) ^ sw) * 16));
; #pragma unroll
;     for (int nb = 0; nb < 2; ++nb) bf[0][nb] = *(const half8*)(s + b_rd + nb * 4096 + (((0 + hh) ^ sw) * 16));
; #pragma unroll
;     for (int ks = 0; ks < 4; ++ks) {
;       if (ks < 3) {
; #pragma unroll
;         for (int mb = 0; mb < MB; ++mb) af[(ks + 1) & 1][mb] = *(const half8*)(s + a_rd + mb * 4096 + (((2 * (ks + 1) + hh) ^ sw) * 16));
; #pragma unroll
;         for (int nb = 0; nb < 2; ++nb) bf[(ks + 1) & 1][nb] = *(const half8*)(s + b_rd + nb * 4096 + (((2 * (ks + 1) + hh) ^ sw) * 16));
;       }
;       if (more) {
;         if (2 * ks < NP) piece(2 * ks, kt + 2, nbuf);
;         if (2 * ks + 1 < NP) piece(2 * ks + 1, kt + 2, nbuf);
;       }
;       __builtin_amdgcn_sched_barrier(0);
;       __builtin_amdgcn_s_setprio(1);
; #pragma unroll
;       for (int mb = 0; mb < MB; ++mb)
; #pragma unroll
;         for (int nb = 0; nb < 2; ++nb)
;           acc[mb][nb] = SWAP ? __builtin_amdgcn_mfma_f32_32x32x16_f16(bf[ks & 1][nb], af[ks & 1][mb], acc[mb][nb], 0, 0, 0)
;                              : __builtin_amdgcn_mfma_f32_32x32x16_f16(af[ks & 1][mb], bf[ks & 1][nb], acc[mb][nb], 0, 0, 0);
;       __builtin_amdgcn_s_setprio(0);
;       __builtin_amdgcn_sched_barrier(0);
;     }
.Lst1_63_skip:
	v_add_u32_e32 v76, v109, v40
	v_add_u32_e32 v80, v43, v40
	v_add_u32_e32 v84, v43, v38
	v_add_u32_e32 v92, v109, v38
	ds_read_b128 v[72:75], v76 offset:8192
	ds_read_b128 v[76:79], v76 offset:12288
	v_lshl_add_u64 v[98:99], v[96:97], 0, s[72:73]
	ds_read_b128 v[80:83], v80
	ds_read_b128 v[84:87], v84
	ds_read_b128 v[88:91], v92 offset:8192
	ds_read_b128 v[92:95], v92 offset:12288
	global_load_lds_dwordx4 v[102:103], off
	s_mov_b32 m0, s1
	s_nop 0
	global_load_lds_dwordx4 v[98:99], off
	s_setprio 1
	s_waitcnt lgkmcnt(0)
	v_mfma_f32_32x32x16_f16 v[16:31], v[72:75], v[80:83], v[16:31]
	v_mfma_f32_32x32x16_f16 v[0:15], v[76:79], v[80:83], v[0:15]
	s_setprio 0
	v_add_u32_e32 v112, 0x4000, v110
	v_add_u32_e32 v111, 0x6000, v110
	v_readfirstlane_b32 s1, v112
	v_add_u32_e32 v72, v43, v37
	v_add_u32_e32 v80, v109, v37
	v_lshl_add_u64 v[102:103], v[96:97], 0, s[88:89]
	s_mov_b32 m0, s1
	v_readfirstlane_b32 s1, v111
	ds_read_b128 v[72:75], v72
	ds_read_b128 v[76:79], v80 offset:8192
	ds_read_b128 v[80:83], v80 offset:12288
	v_lshl_add_u64 v[98:99], v[96:97], 0, s[68:69]
	global_load_lds_dwordx4 v[102:103], off
	s_mov_b32 m0, s1
	s_nop 0
	global_load_lds_dwordx4 v[98:99], off
	s_setprio 1
	v_mfma_f32_32x32x16_f16 v[16:31], v[88:91], v[84:87], v[16:31]
	v_mfma_f32_32x32x16_f16 v[0:15], v[92:95], v[84:87], v[0:15]
	s_setprio 0
	v_add_u32_e32 v43, v43, v36
	v_add_u32_e32 v92, v109, v36
	ds_read_b128 v[84:87], v43
	ds_read_b128 v[88:91], v92 offset:8192
	ds_read_b128 v[92:95], v92 offset:12288
	v_add_u32_e32 v43, 0x8000, v110
	v_lshl_add_u64 v[98:99], v[96:97], 0, s[34:35]
	v_readfirstlane_b32 s1, v43
	s_mov_b32 m0, s1
	s_nop 0
	global_load_lds_dwordx4 v[98:99], off
	s_add_i32 s1, s0, 1
	s_cmp_lg_u32 s0, 2
	s_cselect_b32 s0, s1, 0
	s_mul_i32 s1, s0, 0xa000
	s_add_i32 s24, s1, 0
	s_add_i32 s1, s1, 0xffff6000
	s_cmp_lg_u32 s0, 0
	s_cselect_b32 s1, s1, 0x14000
	v_add_u32_e32 v103, s1, v42
	v_add_u32_e32 v43, s24, v41
	v_add_u32_e32 v102, s24, v39
	v_add_u32_e32 v109, 0x2000, v103
	v_readfirstlane_b32 s1, v103
	v_lshl_add_u64 v[100:101], v[100:101], 0, vcc
	s_mov_b32 m0, s1
	v_readfirstlane_b32 s1, v109
	s_waitcnt vmcnt(5)
	s_waitcnt lgkmcnt(0)
	s_barrier
	s_setprio 1
	v_mfma_f32_32x32x16_f16 v[16:31], v[76:79], v[72:75], v[16:31]
	v_mfma_f32_32x32x16_f16 v[0:15], v[80:83], v[72:75], v[0:15]
	v_mfma_f32_32x32x16_f16 v[16:31], v[88:91], v[84:87], v[16:31]
	v_mfma_f32_32x32x16_f16 v[0:15], v[92:95], v[84:87], v[0:15]
	s_setprio 0
	v_add_u32_e32 v76, v102, v40
	v_add_u32_e32 v80, v43, v40
	v_add_u32_e32 v84, v43, v38
	v_add_u32_e32 v92, v102, v38
	ds_read_b128 v[72:75], v76 offset:8192
	ds_read_b128 v[76:79], v76 offset:12288
	v_lshl_add_u64 v[98:99], v[96:97], 0, s[44:45]
	ds_read_b128 v[80:83], v80
	ds_read_b128 v[84:87], v84
	ds_read_b128 v[88:91], v92 offset:8192
	ds_read_b128 v[92:95], v92 offset:12288
	global_load_lds_dwordx4 v[100:101], off
	s_mov_b32 m0, s1
	s_nop 0
	global_load_lds_dwordx4 v[98:99], off
	s_setprio 1
	s_waitcnt lgkmcnt(0)
	v_mfma_f32_32x32x16_f16 v[16:31], v[72:75], v[80:83], v[16:31]
	v_mfma_f32_32x32x16_f16 v[0:15], v[76:79], v[80:83], v[0:15]
	s_setprio 0
	v_add_u32_e32 v110, 0x4000, v103
	v_add_u32_e32 v109, 0x6000, v103
	v_readfirstlane_b32 s1, v110
	v_add_u32_e32 v72, v43, v37
	v_add_u32_e32 v80, v102, v37
	v_lshl_add_u64 v[100:101], v[96:97], 0, s[54:55]
	s_mov_b32 m0, s1
	v_readfirstlane_b32 s1, v109
	ds_read_b128 v[72:75], v72
	ds_read_b128 v[76:79], v80 offset:8192
	ds_read_b128 v[80:83], v80 offset:12288
	v_lshl_add_u64 v[98:99], v[96:97], 0, s[52:53]
	global_load_lds_dwordx4 v[100:101], off
	s_mov_b32 m0, s1
	s_nop 0
	global_load_lds_dwordx4 v[98:99], off
	s_setprio 1
	v_mfma_f32_32x32x16_f16 v[16:31], v[88:91], v[84:87], v[16:31]
	v_mfma_f32_32x32x16_f16 v[0:15], v[92:95], v[84:87], v[0:15]
	s_setprio 0
	v_add_u32_e32 v43, v43, v36
	v_add_u32_e32 v92, v102, v36
	ds_read_b128 v[84:87], v43
	ds_read_b128 v[88:91], v92 offset:8192
	ds_read_b128 v[92:95], v92 offset:12288
	v_add_u32_e32 v43, 0x8000, v103
	v_lshl_add_u64 v[96:97], v[96:97], 0, s[94:95]
	v_readfirstlane_b32 s1, v43
	s_mov_b32 m0, s1
	s_nop 0
	global_load_lds_dwordx4 v[96:97], off
	s_add_i32 s1, s0, 1
	s_cmp_lg_u32 s0, 2
	s_cselect_b32 s0, s1, 0
	s_add_u32 s2, s2, 0x100
	s_addc_u32 s3, s3, 0
	s_cmpk_eq_i32 s2, 0x700
	s_cbranch_scc0 .Lst1_63_top
	s_waitcnt lgkmcnt(0)
	s_setprio 1
	v_mfma_f32_32x32x16_f16 v[16:31], v[76:79], v[72:75], v[16:31]
	v_mfma_f32_32x32x16_f16 v[0:15], v[80:83], v[72:75], v[0:15]
	v_mfma_f32_32x32x16_f16 v[16:31], v[88:91], v[84:87], v[16:31]
	v_mfma_f32_32x32x16_f16 v[0:15], v[92:95], v[84:87], v[0:15]
	s_setprio 0
; DI float sigmoid_f(float x) { return 1.f / (1.f + __expf(-x)); }
; template <int MB, bool SWAP>
; DI void gemm_kloop(f32x16 (&acc)[MB][2], const h16* __restrict__ A, int lda, const h16* __restrict__ B, int ldb, int K, char* lds) {
;     ...
;   for (int kt = 0; kt < nk; ++kt) {
;     if (kt + 1 < nk) { if (MB == 2) asm volatile("s_waitcnt vmcnt(6)" ::: "memory"); else asm volatile("s_waitcnt vmcnt(5)" ::: "memory"); }
;     else wait_vm0();
;     __syncthreads();
;     const char* s = lds + cur * STAGE;
;     const int nbuf = cur == 0 ? 2 : cur - 1;
;     const bool more = kt + 2 < nk;
;     half8 af[2][MB], bf[2][2];
; #pragma unroll
;     for (int mb = 0; mb < MB; ++mb) af[0][mb] = *(const half8*)(s + a_rd + mb * 4096 + (((0 + hh) ^ sw) * 16));
; #pragma unroll
;     for (int nb = 0; nb < 2; ++nb) bf[0][nb] = *(const half8*)(s + b_rd + nb * 4096 + (((0 + hh) ^ sw) * 16));
; #pragma unroll
;     for (int ks = 0; ks < 4; ++ks) {
;       if (ks < 3) {
; #pragma unroll
;         for (int mb = 0; mb < MB; ++mb) af[(ks + 1) & 1][mb] = *(const half8*)(s + a_rd + mb * 4096 + (((2 * (ks + 1) + hh) ^ sw) * 16));
; #pragma unroll
;         for (int nb = 0; nb < 2; ++nb) bf[(ks + 1) & 1][nb] = *(const half8*)(s + b_rd + nb * 4096 + (((2 * (ks + 1) + hh) ^ sw) * 16));
;       }
;       if (more) {
;         if (2 * ks < NP) piece(2 * ks, kt + 2, nbuf);
;         if (2 * ks + 1 < NP) piece(2 * ks + 1, kt + 2, nbuf);
;       }
;       __builtin_amdgcn_sched_barrier(0);
;       __builtin_amdgcn_s_setprio(1);
; #pragma unroll
;       for (int mb = 0; mb < MB; ++mb)
; #pragma unroll
;         for (int nb = 0; nb < 2; ++nb)
;           acc[mb][nb] = SWAP ? __builtin_amdgcn_mfma_f32_32x32x16_f16(bf[ks & 1][nb], af[ks & 1][mb], acc[mb][nb], 0, 0, 0)
;                              : __builtin_amdgcn_mfma_f32_32x32x16_f16(af[ks & 1][mb], bf[ks & 1][nb], acc[mb][nb], 0, 0, 0);
;       __builtin_amdgcn_s_setprio(0);
;       __builtin_amdgcn_sched_barrier(0);
;     }
;     cur = cur == 2 ? 0 : cur + 1;
;   }
;   __syncthreads();
; template <int MB>
; DI void merge_tile(const Params& P, int layer, size_t row0, int nt, char* smem) {
;     ...
; #pragma unroll
;     for (int mb = 0; mb < MB; ++mb)
; #pragma unroll
;       for (int nb = 0; nb < 2; ++nb)
; #pragma unroll
;         for (int v = 0; v < 16; ++v) gpk[mb][nb][v >> 3][v & 7] = (h16)sigmoid_f(pa2[mb][nb][v]);
.Lst1_63_join:
	v_add_u32_e32 v42, s79, v41
	v_add3_u32 v43, s79, v40, v39
	s_waitcnt vmcnt(5)
	s_waitcnt lgkmcnt(0)
	s_barrier
	ds_read_b128 v[32:35], v43 offset:8192
	ds_read_b128 v[72:75], v43 offset:12288
	v_add_u32_e32 v43, v42, v40
	v_add_u32_e32 v80, v42, v38
	ds_read_b128 v[76:79], v43
	ds_read_b128 v[80:83], v80
	v_add3_u32 v43, s79, v38, v39
	ds_read_b128 v[84:87], v43 offset:8192
	ds_read_b128 v[88:91], v43 offset:12288
	s_cmp_eq_u32 s97, 1
	s_cselect_b32 s0, s12, 0x1ba66000
	s_cmp_lg_u32 s97, 0
	s_cselect_b32 s0, s0, 0x10f66000
	s_setprio 1
	s_waitcnt lgkmcnt(3)
	v_mfma_f32_32x32x16_f16 v[16:31], v[32:35], v[76:79], v[16:31]
	v_mfma_f32_32x32x16_f16 v[0:15], v[72:75], v[76:79], v[0:15]
	s_setprio 0
	v_add_u32_e32 v32, v42, v37
	v_add3_u32 v43, s79, v37, v39
	ds_read_b128 v[32:35], v32
	ds_read_b128 v[72:75], v43 offset:8192
	ds_read_b128 v[76:79], v43 offset:12288
	s_setprio 1
	s_waitcnt lgkmcnt(4)
	v_mfma_f32_32x32x16_f16 v[16:31], v[84:87], v[80:83], v[16:31]
	s_waitcnt lgkmcnt(3)
	v_mfma_f32_32x32x16_f16 v[0:15], v[88:91], v[80:83], v[0:15]
	s_setprio 0
	v_add_u32_e32 v42, v42, v36
	v_add3_u32 v43, s79, v36, v39
	ds_read_b128 v[80:83], v42
	ds_read_b128 v[84:87], v43 offset:8192
	ds_read_b128 v[88:91], v43 offset:12288
	s_setprio 1
	s_waitcnt lgkmcnt(4)
	v_mfma_f32_32x32x16_f16 v[16:31], v[72:75], v[32:35], v[16:31]
	s_waitcnt lgkmcnt(3)
	v_mfma_f32_32x32x16_f16 v[0:15], v[76:79], v[32:35], v[0:15]
	s_setprio 0
	s_setprio 1
	s_waitcnt lgkmcnt(1)
	v_mfma_f32_32x32x16_f16 v[16:31], v[84:87], v[80:83], v[16:31]
	s_waitcnt lgkmcnt(0)
	v_mfma_f32_32x32x16_f16 v[0:15], v[88:91], v[80:83], v[0:15]
	s_setprio 0
	v_add_u32_e32 v89, 0, v39
	v_add_u32_e32 v88, 0, v41
	v_add_u32_e32 v39, v89, v40
	s_waitcnt vmcnt(0)
	s_barrier
	ds_read_b128 v[32:35], v39 offset:8192
	ds_read_b128 v[72:75], v39 offset:12288
	v_add_u32_e32 v39, v88, v40
	v_add_u32_e32 v76, v88, v38
	v_add_u32_e32 v38, v89, v38
	ds_read_b128 v[40:43], v39
	ds_read_b128 v[76:79], v76
	ds_read_b128 v[80:83], v38 offset:8192
	ds_read_b128 v[84:87], v38 offset:12288
	s_setprio 1
	s_waitcnt lgkmcnt(3)
	v_mfma_f32_32x32x16_f16 v[16:31], v[32:35], v[40:43], v[16:31]
	v_mfma_f32_32x32x16_f16 v[0:15], v[72:75], v[40:43], v[0:15]
	s_setprio 0
	v_add_u32_e32 v32, v88, v37
	v_add_u32_e32 v37, v89, v37
	ds_read_b128 v[32:35], v32
	ds_read_b128 v[38:41], v37 offset:8192
	ds_read_b128 v[72:75], v37 offset:12288
	s_setprio 1
	s_waitcnt lgkmcnt(4)
	v_mfma_f32_32x32x16_f16 v[16:31], v[80:83], v[76:79], v[16:31]
	s_waitcnt lgkmcnt(3)
	v_mfma_f32_32x32x16_f16 v[0:15], v[84:87], v[76:79], v[0:15]
	s_setprio 0
	v_add_u32_e32 v37, v88, v36
	v_add_u32_e32 v36, v89, v36
	ds_read_b128 v[76:79], v37
	ds_read_b128 v[80:83], v36 offset:8192
	ds_read_b128 v[84:87], v36 offset:12288
	s_setprio 1
	s_waitcnt lgkmcnt(4)
	v_mfma_f32_32x32x16_f16 v[16:31], v[38:41], v[32:35], v[16:31]
	s_waitcnt lgkmcnt(3)
	v_mfma_f32_32x32x16_f16 v[0:15], v[72:75], v[32:35], v[0:15]
	s_setprio 0
	s_setprio 1
	s_waitcnt lgkmcnt(1)
	v_mfma_f32_32x32x16_f16 v[16:31], v[80:83], v[76:79], v[16:31]
	s_waitcnt lgkmcnt(0)
	v_mfma_f32_32x32x16_f16 v[0:15], v[84:87], v[76:79], v[0:15]
	s_setprio 0
	s_nop 8
	v_mul_f32_e32 v16, 0xbfb8aa3b, v16
	v_exp_f32_e32 v16, v16
	v_mul_f32_e32 v0, 0xbfb8aa3b, v0
	v_exp_f32_e32 v0, v0
	v_add_f32_e32 v16, 1.0, v16
	v_div_scale_f32 v32, s[2:3], v16, v16, 1.0
	v_rcp_f32_e32 v33, v32
	v_add_f32_e32 v0, 1.0, v0
	s_barrier
	v_fma_f32 v34, -v32, v33, 1.0
	v_fmac_f32_e32 v33, v34, v33
	v_div_scale_f32 v34, vcc, 1.0, v16, 1.0
	v_mul_f32_e32 v35, v34, v33
	v_fma_f32 v36, -v32, v35, v34
	v_fmac_f32_e32 v35, v36, v33
	v_fma_f32 v32, -v32, v35, v34
	v_div_fmas_f32 v32, v32, v33, v35
	v_div_fixup_f32 v16, v32, v16, 1.0
	v_cvt_f16_f32_e32 v112, v16
	v_mul_f32_e32 v16, 0xbfb8aa3b, v17
	v_exp_f32_e32 v98, v16
	v_mul_f32_e32 v16, 0xbfb8aa3b, v18
	v_exp_f32_e32 v99, v16
	v_mul_f32_e32 v16, 0xbfb8aa3b, v19
	v_exp_f32_e32 v96, v16
	v_mul_f32_e32 v16, 0xbfb8aa3b, v20
	v_exp_f32_e32 v97, v16
	v_mul_f32_e32 v16, 0xbfb8aa3b, v21
	v_exp_f32_e32 v94, v16
	v_mul_f32_e32 v16, 0xbfb8aa3b, v22
	v_exp_f32_e32 v95, v16
	v_mul_f32_e32 v16, 0xbfb8aa3b, v23
	v_exp_f32_e32 v92, v16
	v_mul_f32_e32 v16, 0xbfb8aa3b, v24
	v_exp_f32_e32 v93, v16
	v_mul_f32_e32 v16, 0xbfb8aa3b, v25
	v_exp_f32_e32 v90, v16
	v_mul_f32_e32 v16, 0xbfb8aa3b, v26
	v_exp_f32_e32 v91, v16
	v_mul_f32_e32 v16, 0xbfb8aa3b, v27
	v_exp_f32_e32 v88, v16
	v_mul_f32_e32 v16, 0xbfb8aa3b, v28
	v_exp_f32_e32 v89, v16
	v_mul_f32_e32 v16, 0xbfb8aa3b, v29
	v_exp_f32_e32 v86, v16
	v_mul_f32_e32 v16, 0xbfb8aa3b, v30
	v_exp_f32_e32 v87, v16
	v_mul_f32_e32 v16, 0xbfb8aa3b, v31
	v_exp_f32_e32 v16, v16
	s_nop 0
	v_add_f32_e32 v16, 1.0, v16
	v_div_scale_f32 v17, s[2:3], v16, v16, 1.0
	v_rcp_f32_e32 v18, v17
	s_nop 0
	v_fma_f32 v19, -v17, v18, 1.0
	v_fmac_f32_e32 v18, v19, v18
	v_div_scale_f32 v19, vcc, 1.0, v16, 1.0
	v_mul_f32_e32 v20, v19, v18
	v_fma_f32 v21, -v17, v20, v19
	v_fmac_f32_e32 v20, v21, v18
	v_fma_f32 v17, -v17, v20, v19
	v_div_fmas_f32 v17, v17, v18, v20
	v_div_fixup_f32 v16, v17, v16, 1.0
	v_cvt_f16_f32_e32 v110, v16
	v_div_scale_f32 v16, s[2:3], v0, v0, 1.0
	v_rcp_f32_e32 v17, v16
	s_nop 0
	v_fma_f32 v18, -v16, v17, 1.0
	v_fmac_f32_e32 v17, v18, v17
	v_div_scale_f32 v18, vcc, 1.0, v0, 1.0
	v_mul_f32_e32 v19, v18, v17
	v_fma_f32 v20, -v16, v19, v18
	v_fmac_f32_e32 v19, v20, v17
	v_fma_f32 v16, -v16, v19, v18
	v_div_fmas_f32 v16, v16, v17, v19
	v_div_fixup_f32 v0, v16, v0, 1.0
	v_cvt_f16_f32_e32 v111, v0
	v_mul_f32_e32 v0, 0xbfb8aa3b, v1
	v_exp_f32_e32 v84, v0
	v_mul_f32_e32 v0, 0xbfb8aa3b, v2
	v_exp_f32_e32 v85, v0
	v_mul_f32_e32 v0, 0xbfb8aa3b, v3
	v_exp_f32_e32 v82, v0
; template <int MB, bool SWAP>
; DI void gemm_kloop(f32x16 (&acc)[MB][2], const h16* __restrict__ A, int lda, const h16* __restrict__ B, int ldb, int K, char* lds) {
;     ...
;   const int tid = otid(), w = tid >> 6, lane = tid & 63;
;   const int wr = w >> 2, wc = w & 3;
;   const int lrow = w * 8 + (lane >> 3), pch = lane & 7;
;   const int gch = pch ^ ((lrow >> 1) & 7);
;   const unsigned voa = (unsigned)(lrow * lda + gch * 8) * 2u, vob = (unsigned)(lrow * ldb + gch * 8) * 2u;
;   const int lofs = lrow * 128 + pch * 16;
;   const int r32 = lane & 31, hh = lane >> 5, sw = (r32 >> 1) & 7;
;   const int a_rd = (wr * 32 * MB + r32) * 128;
;   const int b_rd = A_BYTES + (wc * 64 + r32) * 128;
;   const int nk = K >> 6;
;   constexpr int NP = MB + 4;
;   auto piece = [&](int p, int kt, int buf) {
;     char* s = lds + buf * STAGE;
;     if (p < MB) __builtin_amdgcn_global_load_lds((const unsigned*)((const char*)(A + (size_t)p * 64 * lda + kt * 64) + voa), (unsigned*)(s + p * 8192 + lofs), 16, 0, 0);
;     else __builtin_amdgcn_global_load_lds((const unsigned*)((const char*)(B + (size_t)(p - MB) * 64 * ldb + kt * 64) + vob), (unsigned*)(s + A_BYTES + (p - MB) * 8192 + lofs), 16, 0, 0);
;   };
;   wait_vm0();
; #pragma unroll
;   for (int p = 0; p < NP; ++p) piece(p, 0, 0);
; #pragma unroll
;   for (int p = 0; p < NP; ++p) piece(p, 1, 1);
;   int cur = 0;
;   for (int kt = 0; kt < nk; ++kt) {
;     if (kt + 1 < nk) { if (MB == 2) asm volatile("s_waitcnt vmcnt(6)" ::: "memory"); else asm volatile("s_waitcnt vmcnt(5)" ::: "memory"); }
;     else wait_vm0();
;     __syncthreads();
;     const char* s = lds + cur * STAGE;
;     const int nbuf = cur == 0 ? 2 : cur - 1;
;     const bool more = kt + 2 < nk;
;     half8 af[2][MB], bf[2][2];
; #pragma unroll
;     for (int mb = 0; mb < MB; ++mb) af[0][mb] = *(const half8*)(s + a_rd + mb * 4096 + (((0 + hh) ^ sw) * 16));
; #pragma unroll
;     for (int nb = 0; nb < 2; ++nb) bf[0][nb] = *(const half8*)(s + b_rd + nb * 4096 + (((0 + hh) ^ sw) * 16));
; #pragma unroll
; template <int MB>
; DI void merge_tile(const Params& P, int layer, size_t row0, int nt, char* smem) {
;     ...
;         for (int v = 0; v < 16; ++v) gpk[mb][nb][v >> 3][v & 7] = (h16)sigmoid_f(pa2[mb][nb][v]);
;     zero_acc<MB>(pa2);
;     gemm_kloop<MB, true>(pa2, yn + row0 * LDY, LDY, wbrT + (size_t)(n * 1024 + nt * 256) * LDY, LDY, WB, smem);
	v_mul_f32_e32 v0, 0xbfb8aa3b, v4
	v_exp_f32_e32 v83, v0
	v_mul_f32_e32 v0, 0xbfb8aa3b, v5
	v_exp_f32_e32 v80, v0
	v_mul_f32_e32 v0, 0xbfb8aa3b, v6
	v_exp_f32_e32 v81, v0
	v_mul_f32_e32 v0, 0xbfb8aa3b, v7
	v_exp_f32_e32 v78, v0
	v_mul_f32_e32 v0, 0xbfb8aa3b, v8
	v_exp_f32_e32 v79, v0
	v_mul_f32_e32 v0, 0xbfb8aa3b, v9
	v_exp_f32_e32 v76, v0
	v_mul_f32_e32 v0, 0xbfb8aa3b, v10
	v_exp_f32_e32 v77, v0
	v_mul_f32_e32 v0, 0xbfb8aa3b, v11
	v_exp_f32_e32 v74, v0
	v_mul_f32_e32 v0, 0xbfb8aa3b, v12
	v_exp_f32_e32 v75, v0
	v_mul_f32_e32 v0, 0xbfb8aa3b, v13
	v_exp_f32_e32 v72, v0
	v_mul_f32_e32 v0, 0xbfb8aa3b, v14
	v_exp_f32_e32 v73, v0
	v_mul_f32_e32 v0, 0xbfb8aa3b, v15
	v_exp_f32_e32 v0, v0
	s_nop 0
	v_add_f32_e32 v0, 1.0, v0
	v_div_scale_f32 v1, s[2:3], v0, v0, 1.0
	v_rcp_f32_e32 v2, v1
	s_add_u32 s2, s87, s0
	s_addc_u32 s3, s96, 0
	s_or_b32 s0, s51, s81
	v_fma_f32 v3, -v1, v2, 1.0
	v_fmac_f32_e32 v2, v3, v2
	v_div_scale_f32 v3, vcc, 1.0, v0, 1.0
	v_mul_f32_e32 v4, v3, v2
	v_fma_f32 v5, -v1, v4, v3
	v_fmac_f32_e32 v4, v5, v2
	v_fma_f32 v1, -v1, v4, v3
	v_div_fmas_f32 v1, v1, v2, v4
	v_div_fixup_f32 v0, v1, v0, 1.0
	v_mov_b32_e32 v2, v208
	v_cvt_f16_f32_e32 v109, v0
	s_mul_i32 s84, s0, 0x240
	v_ashrrev_i32_e32 v0, 3, v2
	v_bfe_u32 v1, v2, 3, 3
	v_and_or_b32 v1, v0, -8, v1
	v_lshrrev_b32_e32 v3, 1, v1
	v_xor_b32_e32 v3, v3, v2
	v_mul_lo_u32 v4, v1, s13
	v_lshlrev_b32_e32 v3, 3, v3
	v_and_or_b32 v3, v3, 56, v4
	v_lshlrev_b32_e32 v128, 1, v3
	v_lshlrev_b32_e32 v3, 4, v2
	v_and_b32_e32 v3, 0x70, v3
	v_lshl_or_b32 v140, v1, 7, v3
	v_and_b32_e32 v1, 31, v2
	s_lshl_b64 s[0:1], s[84:85], 1
	v_and_or_b32 v4, v0, s16, v1
	v_lshlrev_b32_e32 v0, 7, v2
	v_add_u32_e32 v118, 0, v140
	s_add_u32 s24, s74, s0
	v_and_b32_e32 v5, 0x6f80, v0
	v_readfirstlane_b32 s0, v118
	v_add_u32_e32 v0, 0x2000, v118
	s_addc_u32 s25, s75, s1
	s_waitcnt vmcnt(0)
	s_mov_b32 m0, s0
	v_readfirstlane_b32 s45, v0
	v_add_u32_e32 v6, 0x4000, v118
	v_lshl_add_u64 v[100:101], s[24:25], 0, v[128:129]
	v_lshl_add_u64 v[102:103], s[2:3], 0, v[128:129]
	global_load_lds_dwordx4 v128, s[2:3]
	s_mov_b32 m0, s45
	s_mov_b64 s[2:3], 0x12000
	v_readfirstlane_b32 s44, v6
	v_add_u32_e32 v6, 0x6000, v118
	global_load_lds_dwordx4 v128, s[24:25]
	v_lshl_add_u64 v[0:1], v[100:101], 0, s[2:3]
	s_mov_b32 m0, s44
	s_mov_b64 s[2:3], 0x24000
	v_readfirstlane_b32 s77, v6
	v_add_u32_e32 v6, 0x8000, v118
	global_load_lds_dwordx4 v[0:1], off
	v_lshl_add_u64 v[0:1], v[100:101], 0, s[2:3]
	s_mov_b32 m0, s77
	s_mov_b64 s[2:3], 0x36000
	v_readfirstlane_b32 s50, v6
	v_lshlrev_b32_e32 v120, 7, v4
	v_add_u32_e32 v4, 0xa000, v118
	global_load_lds_dwordx4 v[0:1], off
	v_lshl_add_u64 v[0:1], v[100:101], 0, s[2:3]
	s_mov_b32 m0, s50
	v_readfirstlane_b32 s84, v4
	v_add_u32_e32 v4, 0xc000, v118
	global_load_lds_dwordx4 v[0:1], off
	v_lshl_add_u64 v[0:1], v[102:103], 0, s[22:23]
	s_mov_b32 m0, s84
	v_readfirstlane_b32 s51, v4
	global_load_lds_dwordx4 v[0:1], off
	v_lshl_add_u64 v[0:1], v[100:101], 0, s[22:23]
	s_mov_b32 m0, s51
	s_mov_b64 s[2:3], 0x12080
	v_add_u32_e32 v4, 0xe000, v118
	global_load_lds_dwordx4 v[0:1], off
	v_lshl_add_u64 v[0:1], v[100:101], 0, s[2:3]
	v_readfirstlane_b32 s3, v4
	v_add_u32_e32 v4, s8, v140
	s_mov_b32 m0, s3
	s_mov_b64 s[24:25], 0x24080
	v_readfirstlane_b32 s1, v4
	v_add_u32_e32 v4, s9, v140
	global_load_lds_dwordx4 v[0:1], off
	v_lshl_add_u64 v[0:1], v[100:101], 0, s[24:25]
	s_mov_b32 m0, s1
	s_mov_b64 s[24:25], 0x36080
	v_readfirstlane_b32 s2, v4
	v_lshrrev_b32_e32 v3, 1, v2
	v_bfe_u32 v6, v2, 5, 1
	global_load_lds_dwordx4 v[0:1], off
	v_lshl_add_u64 v[0:1], v[100:101], 0, s[24:25]
	s_mov_b32 m0, s2
	v_add_u32_e32 v16, s79, v140
	global_load_lds_dwordx4 v[0:1], off
	v_bfe_u32 v0, v2, 1, 3
	v_bitop3_b32 v1, v6, v3, 7 bitop3:0x78
	v_lshlrev_b32_e32 v128, 4, v1
	v_bitop3_b32 v1, v6, v0, 2 bitop3:0x36
	v_lshlrev_b32_e32 v141, 4, v1
	v_add_u32_e32 v142, 0, v120
	v_add_u32_e32 v143, 0, v5
	v_add_u32_e32 v126, s10, v140
	v_readfirstlane_b32 s33, v16
	v_bitop3_b32 v1, v6, v0, 4 bitop3:0x36
	v_bitop3_b32 v0, v6, v0, 6 bitop3:0x36
	v_add_u32_e32 v113, v143, v128
	v_add_u32_e32 v114, v142, v128
	v_add_u32_e32 v115, v142, v141
	v_add_u32_e32 v116, v143, v141
	v_lshl_add_u64 v[14:15], v[102:103], 0, s[30:31]
	s_mov_b32 m0, s33
	v_readfirstlane_b32 s1, v126
	v_add_u32_e32 v117, 0x2000, v5
	v_lshlrev_b32_e32 v121, 4, v1
	v_lshlrev_b32_e32 v119, 4, v0
	s_waitcnt vmcnt(5)
	s_waitcnt lgkmcnt(0)
	s_barrier
	ds_read_b128 v[0:3], v113 offset:8192
	ds_read_b128 v[4:7], v113 offset:12288
	ds_read_b128 v[8:11], v114
	ds_read_b128 v[32:35], v115
	ds_read_b128 v[40:43], v116 offset:8192
	ds_read_b128 v[36:39], v116 offset:12288
	v_lshl_add_u64 v[12:13], v[100:101], 0, s[30:31]
	global_load_lds_dwordx4 v[14:15], off
	s_mov_b32 m0, s1
	s_nop 0
	global_load_lds_dwordx4 v[12:13], off
	s_setprio 1
	s_waitcnt lgkmcnt(0)
	v_mfma_f32_32x32x16_f16 v[16:31], v[0:3], v[8:11], 0
	v_mfma_f32_32x32x16_f16 v[0:15], v[4:7], v[8:11], 0
	s_setprio 0
	s_mov_b64 s[24:25], 0x24100
	v_add_u32_e32 v146, 0x4000, v126
	v_lshl_add_u64 v[126:127], v[100:101], 0, s[24:25]
	s_add_i32 s24, 0, 0x18000
	v_add_u32_e32 v147, s24, v140
	v_add_u32_e32 v144, v142, v121
	v_readfirstlane_b32 s78, v147
	v_lshl_add_u64 v[138:139], v[100:101], 0, s[92:93]
	s_mov_b32 m0, s78
	v_readfirstlane_b32 s24, v146
	v_add_u32_e32 v145, v143, v121
	ds_read_b128 v[122:125], v144
	ds_read_b128 v[130:133], v145 offset:8192
	ds_read_b128 v[134:137], v145 offset:12288
	global_load_lds_dwordx4 v[138:139], off
	s_mov_b32 m0, s24
	s_nop 0
	global_load_lds_dwordx4 v[126:127], off
	s_setprio 1
	v_mfma_f32_32x32x16_f16 v[16:31], v[40:43], v[32:35], v[16:31]
	v_mfma_f32_32x32x16_f16 v[0:15], v[36:39], v[32:35], v[0:15]
	s_setprio 0
	v_add_u32_e32 v138, s17, v140
	s_mov_b64 s[52:53], 0x36100
	v_readfirstlane_b32 s25, v138
	v_add_u32_e32 v142, v142, v119
	v_lshl_add_u64 v[126:127], v[100:101], 0, s[52:53]
	s_mov_b32 m0, s25
	v_add_u32_e32 v143, v143, v119
	ds_read_b128 v[32:35], v142
	ds_read_b128 v[36:39], v143 offset:8192
	ds_read_b128 v[40:43], v143 offset:12288
	global_load_lds_dwordx4 v[126:127], off
	s_setprio 1
	s_waitcnt lgkmcnt(0)
	v_mfma_f32_32x32x16_f16 v[16:31], v[130:133], v[122:125], v[16:31]
	v_mfma_f32_32x32x16_f16 v[0:15], v[134:137], v[122:125], v[0:15]
	s_setprio 0
	s_setprio 1
	v_mfma_f32_32x32x16_f16 v[16:31], v[36:39], v[32:35], v[16:31]
	v_mfma_f32_32x32x16_f16 v[0:15], v[40:43], v[32:35], v[0:15]
	s_setprio 0
	s_mov_b64 s[52:53], 0x180
	s_mov_b32 m0, s0
	v_lshl_add_u64 v[138:139], v[102:103], 0, s[52:53]
	s_waitcnt vmcnt(5)
	s_waitcnt lgkmcnt(0)
	s_barrier
; DI void wait_vm0() { asm volatile("s_waitcnt vmcnt(0)" ::: "memory"); }
; template <int MB, bool SWAP>
; DI void gemm_kloop(f32x16 (&acc)[MB][2], const h16* __restrict__ A, int lda, const h16* __restrict__ B, int ldb, int K, char* lds) {
;     ...
;   for (int kt = 0; kt < nk; ++kt) {
;     if (kt + 1 < nk) { if (MB == 2) asm volatile("s_waitcnt vmcnt(6)" ::: "memory"); else asm volatile("s_waitcnt vmcnt(5)" ::: "memory"); }
;     else wait_vm0();
;     __syncthreads();
;     const char* s = lds + cur * STAGE;
;     const int nbuf = cur == 0 ? 2 : cur - 1;
;     const bool more = kt + 2 < nk;
;     half8 af[2][MB], bf[2][2];
; #pragma unroll
;     for (int mb = 0; mb < MB; ++mb) af[0][mb] = *(const half8*)(s + a_rd + mb * 4096 + (((0 + hh) ^ sw) * 16));
; #pragma unroll
;     for (int nb = 0; nb < 2; ++nb) bf[0][nb] = *(const half8*)(s + b_rd + nb * 4096 + (((0 + hh) ^ sw) * 16));
; #pragma unroll
;     for (int ks = 0; ks < 4; ++ks) {
;       if (ks < 3) {
; #pragma unroll
;         for (int mb = 0; mb < MB; ++mb) af[(ks + 1) & 1][mb] = *(const half8*)(s + a_rd + mb * 4096 + (((2 * (ks + 1) + hh) ^ sw) * 16));
; #pragma unroll
;         for (int nb = 0; nb < 2; ++nb) bf[(ks + 1) & 1][nb] = *(const half8*)(s + b_rd + nb * 4096 + (((2 * (ks + 1) + hh) ^ sw) * 16));
;       }
;       if (more) {
;         if (2 * ks < NP) piece(2 * ks, kt + 2, nbuf);
;         if (2 * ks + 1 < NP) piece(2 * ks + 1, kt + 2, nbuf);
;       }
;       __builtin_amdgcn_sched_barrier(0);
;       __builtin_amdgcn_s_setprio(1);
; #pragma unroll
;       for (int mb = 0; mb < MB; ++mb)
; #pragma unroll
;         for (int nb = 0; nb < 2; ++nb)
;           acc[mb][nb] = SWAP ? __builtin_amdgcn_mfma_f32_32x32x16_f16(bf[ks & 1][nb], af[ks & 1][mb], acc[mb][nb], 0, 0, 0)
;                              : __builtin_amdgcn_mfma_f32_32x32x16_f16(af[ks & 1][mb], bf[ks & 1][nb], acc[mb][nb], 0, 0, 0);
;       __builtin_amdgcn_s_setprio(0);
;       __builtin_amdgcn_sched_barrier(0);
;     }
	ds_read_b128 v[32:35], v113 offset:49152
	ds_read_b128 v[36:39], v113 offset:53248
	ds_read_b128 v[40:43], v114 offset:40960
	ds_read_b128 v[122:125], v115 offset:40960
	ds_read_b128 v[130:133], v116 offset:49152
	ds_read_b128 v[134:137], v116 offset:53248
	v_lshl_add_u64 v[126:127], v[100:101], 0, s[52:53]
	global_load_lds_dwordx4 v[138:139], off
	s_mov_b32 m0, s45
	s_nop 0
	global_load_lds_dwordx4 v[126:127], off
	s_setprio 1
	s_waitcnt lgkmcnt(0)
	v_mfma_f32_32x32x16_f16 v[16:31], v[32:35], v[40:43], v[16:31]
	v_mfma_f32_32x32x16_f16 v[0:15], v[36:39], v[40:43], v[0:15]
	s_setprio 0
	s_mov_b64 s[52:53], 0x24180
	v_lshl_add_u64 v[126:127], v[100:101], 0, s[52:53]
	s_mov_b64 s[52:53], 0x12180
	s_mov_b32 m0, s44
	v_lshl_add_u64 v[138:139], v[100:101], 0, s[52:53]
	ds_read_b128 v[32:35], v144 offset:40960
	ds_read_b128 v[36:39], v145 offset:49152
	ds_read_b128 v[40:43], v145 offset:53248
	global_load_lds_dwordx4 v[138:139], off
	s_mov_b32 m0, s77
	s_nop 0
	global_load_lds_dwordx4 v[126:127], off
	s_setprio 1
	v_mfma_f32_32x32x16_f16 v[16:31], v[130:133], v[122:125], v[16:31]
	v_mfma_f32_32x32x16_f16 v[0:15], v[134:137], v[122:125], v[0:15]
	s_setprio 0
	s_mov_b64 s[52:53], 0x36180
	v_lshl_add_u64 v[126:127], v[100:101], 0, s[52:53]
	s_mov_b32 m0, s50
	ds_read_b128 v[122:125], v142 offset:40960
	ds_read_b128 v[130:133], v143 offset:49152
	ds_read_b128 v[134:137], v143 offset:53248
	global_load_lds_dwordx4 v[126:127], off
	s_setprio 1
	s_waitcnt lgkmcnt(0)
	v_mfma_f32_32x32x16_f16 v[16:31], v[36:39], v[32:35], v[16:31]
	v_mfma_f32_32x32x16_f16 v[0:15], v[40:43], v[32:35], v[0:15]
	s_setprio 0
	s_setprio 1
	v_mfma_f32_32x32x16_f16 v[16:31], v[130:133], v[122:125], v[16:31]
	v_mfma_f32_32x32x16_f16 v[0:15], v[134:137], v[122:125], v[0:15]
	s_setprio 0
	v_add_u32_e32 v140, s79, v120
	s_mov_b64 s[52:53], 0x200
	s_mov_b32 m0, s84
	v_add3_u32 v146, s79, v128, v117
	v_add_u32_e32 v128, v140, v128
	v_add_u32_e32 v147, v140, v141
	v_add3_u32 v141, s79, v141, v117
	v_lshl_add_u64 v[138:139], v[102:103], 0, s[52:53]
	s_waitcnt vmcnt(5)
	s_waitcnt lgkmcnt(0)
	s_barrier
	ds_read_b128 v[32:35], v146
	ds_read_b128 v[36:39], v146 offset:4096
	ds_read_b128 v[40:43], v128
	ds_read_b128 v[122:125], v147
	ds_read_b128 v[130:133], v141
	ds_read_b128 v[134:137], v141 offset:4096
	v_lshl_add_u64 v[126:127], v[100:101], 0, s[52:53]
	global_load_lds_dwordx4 v[138:139], off
	s_mov_b32 m0, s51
	s_nop 0
	global_load_lds_dwordx4 v[126:127], off
	s_setprio 1
	s_waitcnt lgkmcnt(0)
	v_mfma_f32_32x32x16_f16 v[16:31], v[32:35], v[40:43], v[16:31]
	v_mfma_f32_32x32x16_f16 v[0:15], v[36:39], v[40:43], v[0:15]
	s_setprio 0
	s_mov_b64 s[52:53], 0x24200
	v_add_u32_e32 v138, v140, v121
	v_add3_u32 v139, s79, v121, v117
	v_add_u32_e32 v118, 0x10000, v118
	v_lshl_add_u64 v[120:121], v[100:101], 0, s[52:53]
	s_mov_b64 s[52:53], 0x12200
	s_mov_b32 m0, s3
	v_lshl_add_u64 v[126:127], v[100:101], 0, s[52:53]
	v_readfirstlane_b32 s52, v118
	ds_read_b128 v[32:35], v138
	ds_read_b128 v[36:39], v139
	ds_read_b128 v[40:43], v139 offset:4096
	global_load_lds_dwordx4 v[126:127], off
	s_mov_b32 m0, s52
	s_nop 0
	global_load_lds_dwordx4 v[120:121], off
	s_setprio 1
	v_mfma_f32_32x32x16_f16 v[16:31], v[130:133], v[122:125], v[16:31]
	v_mfma_f32_32x32x16_f16 v[0:15], v[134:137], v[122:125], v[0:15]
	s_setprio 0
	s_mov_b64 s[54:55], 0x36200
	v_add_u32_e32 v136, v140, v119
	v_lshl_add_u64 v[126:127], v[100:101], 0, s[54:55]
	s_mov_b32 m0, s2
	v_add3_u32 v117, s79, v119, v117
	ds_read_b128 v[118:121], v136
	ds_read_b128 v[122:125], v117
	ds_read_b128 v[130:133], v117 offset:4096
	global_load_lds_dwordx4 v[126:127], off
	s_setprio 1
	s_waitcnt lgkmcnt(0)
	v_mfma_f32_32x32x16_f16 v[16:31], v[36:39], v[32:35], v[16:31]
	v_mfma_f32_32x32x16_f16 v[0:15], v[40:43], v[32:35], v[0:15]
	s_setprio 0
	s_setprio 1
	v_mfma_f32_32x32x16_f16 v[16:31], v[122:125], v[118:121], v[16:31]
	v_mfma_f32_32x32x16_f16 v[0:15], v[130:133], v[118:121], v[0:15]
	s_setprio 0
	s_mov_b64 s[54:55], 0x280
	s_mov_b32 m0, s33
	v_lshl_add_u64 v[134:135], v[102:103], 0, s[54:55]
	s_waitcnt vmcnt(5)
	s_waitcnt lgkmcnt(0)
	s_barrier
	ds_read_b128 v[32:35], v113 offset:8192
	ds_read_b128 v[36:39], v113 offset:12288
	ds_read_b128 v[40:43], v114
	ds_read_b128 v[118:121], v115
	ds_read_b128 v[122:125], v116 offset:8192
	ds_read_b128 v[130:133], v116 offset:12288
	v_lshl_add_u64 v[126:127], v[100:101], 0, s[54:55]
	global_load_lds_dwordx4 v[134:135], off
	s_mov_b32 m0, s1
	s_nop 0
	global_load_lds_dwordx4 v[126:127], off
	s_setprio 1
	s_waitcnt lgkmcnt(0)
	v_mfma_f32_32x32x16_f16 v[16:31], v[32:35], v[40:43], v[16:31]
	v_mfma_f32_32x32x16_f16 v[0:15], v[36:39], v[40:43], v[0:15]
	s_setprio 0
	s_mov_b64 s[54:55], 0x24280
	v_lshl_add_u64 v[126:127], v[100:101], 0, s[54:55]
	s_mov_b64 s[54:55], 0x12280
	s_mov_b32 m0, s78
	v_lshl_add_u64 v[134:135], v[100:101], 0, s[54:55]
	ds_read_b128 v[32:35], v144
	ds_read_b128 v[36:39], v145 offset:8192
	ds_read_b128 v[40:43], v145 offset:12288
	global_load_lds_dwordx4 v[134:135], off
	s_mov_b32 m0, s24
	s_nop 0
	global_load_lds_dwordx4 v[126:127], off
	s_setprio 1
	v_mfma_f32_32x32x16_f16 v[16:31], v[122:125], v[118:121], v[16:31]
	v_mfma_f32_32x32x16_f16 v[0:15], v[130:133], v[118:121], v[0:15]
	s_setprio 0
	s_mov_b64 s[54:55], 0x36280
	v_lshl_add_u64 v[126:127], v[100:101], 0, s[54:55]
	s_mov_b32 m0, s25
	ds_read_b128 v[118:121], v142
	ds_read_b128 v[122:125], v143 offset:8192
	ds_read_b128 v[130:133], v143 offset:12288
	global_load_lds_dwordx4 v[126:127], off
	s_setprio 1
	s_waitcnt lgkmcnt(0)
	v_mfma_f32_32x32x16_f16 v[16:31], v[36:39], v[32:35], v[16:31]
	v_mfma_f32_32x32x16_f16 v[0:15], v[40:43], v[32:35], v[0:15]
	s_setprio 0
	s_setprio 1
	v_mfma_f32_32x32x16_f16 v[16:31], v[122:125], v[118:121], v[16:31]
	v_mfma_f32_32x32x16_f16 v[0:15], v[130:133], v[118:121], v[0:15]
	s_setprio 0
	s_mov_b32 m0, s0
	s_mov_b64 s[0:1], 0x300
	v_lshl_add_u64 v[134:135], v[102:103], 0, s[0:1]
	s_waitcnt vmcnt(5)
	s_waitcnt lgkmcnt(0)
	s_barrier
; DI void wait_vm0() { asm volatile("s_waitcnt vmcnt(0)" ::: "memory"); }
; template <int MB, bool SWAP>
; DI void gemm_kloop(f32x16 (&acc)[MB][2], const h16* __restrict__ A, int lda, const h16* __restrict__ B, int ldb, int K, char* lds) {
;     ...
;   for (int kt = 0; kt < nk; ++kt) {
;     if (kt + 1 < nk) { if (MB == 2) asm volatile("s_waitcnt vmcnt(6)" ::: "memory"); else asm volatile("s_waitcnt vmcnt(5)" ::: "memory"); }
;     else wait_vm0();
;     __syncthreads();
;     const char* s = lds + cur * STAGE;
;     const int nbuf = cur == 0 ? 2 : cur - 1;
;     const bool more = kt + 2 < nk;
;     half8 af[2][MB], bf[2][2];
; #pragma unroll
;     for (int mb = 0; mb < MB; ++mb) af[0][mb] = *(const half8*)(s + a_rd + mb * 4096 + (((0 + hh) ^ sw) * 16));
; #pragma unroll
;     for (int nb = 0; nb < 2; ++nb) bf[0][nb] = *(const half8*)(s + b_rd + nb * 4096 + (((0 + hh) ^ sw) * 16));
; #pragma unroll
;     for (int ks = 0; ks < 4; ++ks) {
;       if (ks < 3) {
; #pragma unroll
;         for (int mb = 0; mb < MB; ++mb) af[(ks + 1) & 1][mb] = *(const half8*)(s + a_rd + mb * 4096 + (((2 * (ks + 1) + hh) ^ sw) * 16));
; #pragma unroll
;         for (int nb = 0; nb < 2; ++nb) bf[(ks + 1) & 1][nb] = *(const half8*)(s + b_rd + nb * 4096 + (((2 * (ks + 1) + hh) ^ sw) * 16));
;       }
;       if (more) {
;         if (2 * ks < NP) piece(2 * ks, kt + 2, nbuf);
;         if (2 * ks + 1 < NP) piece(2 * ks + 1, kt + 2, nbuf);
;       }
;       __builtin_amdgcn_sched_barrier(0);
;       __builtin_amdgcn_s_setprio(1);
; #pragma unroll
;       for (int mb = 0; mb < MB; ++mb)
; #pragma unroll
;         for (int nb = 0; nb < 2; ++nb)
;           acc[mb][nb] = SWAP ? __builtin_amdgcn_mfma_f32_32x32x16_f16(bf[ks & 1][nb], af[ks & 1][mb], acc[mb][nb], 0, 0, 0)
;                              : __builtin_amdgcn_mfma_f32_32x32x16_f16(af[ks & 1][mb], bf[ks & 1][nb], acc[mb][nb], 0, 0, 0);
;       __builtin_amdgcn_s_setprio(0);
;       __builtin_amdgcn_sched_barrier(0);
;     }
;     cur = cur == 2 ? 0 : cur + 1;
;   }
;   __syncthreads();
	ds_read_b128 v[32:35], v113 offset:49152
	ds_read_b128 v[36:39], v113 offset:53248
	ds_read_b128 v[40:43], v114 offset:40960
	ds_read_b128 v[118:121], v115 offset:40960
	ds_read_b128 v[122:125], v116 offset:49152
	ds_read_b128 v[130:133], v116 offset:53248
	v_lshl_add_u64 v[126:127], v[100:101], 0, s[0:1]
	global_load_lds_dwordx4 v[134:135], off
	s_mov_b32 m0, s45
	s_nop 0
	global_load_lds_dwordx4 v[126:127], off
	s_setprio 1
	s_waitcnt lgkmcnt(0)
	v_mfma_f32_32x32x16_f16 v[16:31], v[32:35], v[40:43], v[16:31]
	v_mfma_f32_32x32x16_f16 v[0:15], v[36:39], v[40:43], v[0:15]
	s_setprio 0
	s_mov_b64 s[0:1], 0x24300
	v_lshl_add_u64 v[126:127], v[100:101], 0, s[0:1]
	s_mov_b64 s[0:1], 0x12300
	s_mov_b32 m0, s44
	v_lshl_add_u64 v[134:135], v[100:101], 0, s[0:1]
	ds_read_b128 v[32:35], v144 offset:40960
	ds_read_b128 v[36:39], v145 offset:49152
	ds_read_b128 v[40:43], v145 offset:53248
	global_load_lds_dwordx4 v[134:135], off
	s_mov_b32 m0, s77
	s_nop 0
	global_load_lds_dwordx4 v[126:127], off
	s_setprio 1
	v_mfma_f32_32x32x16_f16 v[16:31], v[122:125], v[118:121], v[16:31]
	v_mfma_f32_32x32x16_f16 v[0:15], v[130:133], v[118:121], v[0:15]
	s_setprio 0
	s_mov_b64 s[0:1], 0x36300
	v_lshl_add_u64 v[126:127], v[100:101], 0, s[0:1]
	s_mov_b32 m0, s50
	ds_read_b128 v[118:121], v142 offset:40960
	ds_read_b128 v[122:125], v143 offset:49152
	ds_read_b128 v[130:133], v143 offset:53248
	global_load_lds_dwordx4 v[126:127], off
	s_setprio 1
	s_waitcnt lgkmcnt(0)
	v_mfma_f32_32x32x16_f16 v[16:31], v[36:39], v[32:35], v[16:31]
	v_mfma_f32_32x32x16_f16 v[0:15], v[40:43], v[32:35], v[0:15]
	s_setprio 0
	s_setprio 1
	v_mfma_f32_32x32x16_f16 v[16:31], v[122:125], v[118:121], v[16:31]
	v_mfma_f32_32x32x16_f16 v[0:15], v[130:133], v[118:121], v[0:15]
	s_setprio 0
	s_mov_b64 s[0:1], 0x380
	s_mov_b32 m0, s84
	v_lshl_add_u64 v[102:103], v[102:103], 0, s[0:1]
	s_waitcnt vmcnt(5)
	s_waitcnt lgkmcnt(0)
	s_barrier
	ds_read_b128 v[32:35], v146
	ds_read_b128 v[36:39], v146 offset:4096
	ds_read_b128 v[40:43], v128
	ds_read_b128 v[118:121], v147
	ds_read_b128 v[122:125], v141
	ds_read_b128 v[130:133], v141 offset:4096
	v_lshl_add_u64 v[126:127], v[100:101], 0, s[0:1]
	global_load_lds_dwordx4 v[102:103], off
	s_mov_b32 m0, s51
	s_nop 0
	global_load_lds_dwordx4 v[126:127], off
	s_setprio 1
	s_waitcnt lgkmcnt(0)
	v_mfma_f32_32x32x16_f16 v[16:31], v[32:35], v[40:43], v[16:31]
	v_mfma_f32_32x32x16_f16 v[0:15], v[36:39], v[40:43], v[0:15]
	s_setprio 0
	s_mov_b64 s[0:1], 0x24380
	v_lshl_add_u64 v[102:103], v[100:101], 0, s[0:1]
	s_mov_b64 s[0:1], 0x12380
	s_mov_b32 m0, s3
	v_lshl_add_u64 v[126:127], v[100:101], 0, s[0:1]
	ds_read_b128 v[32:35], v138
	ds_read_b128 v[36:39], v139
	ds_read_b128 v[40:43], v139 offset:4096
	global_load_lds_dwordx4 v[126:127], off
	s_mov_b32 m0, s52
	s_nop 0
	global_load_lds_dwordx4 v[102:103], off
	s_setprio 1
	v_mfma_f32_32x32x16_f16 v[16:31], v[122:125], v[118:121], v[16:31]
	v_mfma_f32_32x32x16_f16 v[0:15], v[130:133], v[118:121], v[0:15]
	s_setprio 0
	s_mov_b64 s[0:1], 0x36380
	v_lshl_add_u64 v[100:101], v[100:101], 0, s[0:1]
	s_mov_b32 m0, s2
	ds_read_b128 v[118:121], v136
	ds_read_b128 v[122:125], v117
	ds_read_b128 v[130:133], v117 offset:4096
	global_load_lds_dwordx4 v[100:101], off
	s_setprio 1
	s_waitcnt lgkmcnt(0)
	v_mfma_f32_32x32x16_f16 v[16:31], v[36:39], v[32:35], v[16:31]
	v_mfma_f32_32x32x16_f16 v[0:15], v[40:43], v[32:35], v[0:15]
	s_setprio 0
	s_setprio 1
	v_mfma_f32_32x32x16_f16 v[16:31], v[122:125], v[118:121], v[16:31]
	v_mfma_f32_32x32x16_f16 v[0:15], v[130:133], v[118:121], v[0:15]
	s_setprio 0
	s_waitcnt vmcnt(5)
	s_waitcnt lgkmcnt(0)
	s_barrier
	ds_read_b128 v[32:35], v116 offset:8192
	ds_read_b128 v[36:39], v116 offset:12288
	ds_read_b128 v[40:43], v115
	ds_read_b128 v[100:103], v114
	ds_read_b128 v[118:121], v113 offset:12288
	ds_read_b128 v[122:125], v113 offset:8192
	s_setprio 1
	s_waitcnt lgkmcnt(0)
	v_mfma_f32_32x32x16_f16 v[16:31], v[122:125], v[100:103], v[16:31]
	v_mfma_f32_32x32x16_f16 v[0:15], v[118:121], v[100:103], v[0:15]
	s_setprio 0
	ds_read_b128 v[100:103], v144
	ds_read_b128 v[118:121], v145 offset:8192
	ds_read_b128 v[122:125], v145 offset:12288
	s_setprio 1
	v_mfma_f32_32x32x16_f16 v[16:31], v[32:35], v[40:43], v[16:31]
	v_mfma_f32_32x32x16_f16 v[0:15], v[36:39], v[40:43], v[0:15]
	s_setprio 0
	ds_read_b128 v[32:35], v143 offset:12288
	ds_read_b128 v[36:39], v143 offset:8192
	ds_read_b128 v[40:43], v142
	s_setprio 1
	s_waitcnt lgkmcnt(4)
	v_mfma_f32_32x32x16_f16 v[16:31], v[118:121], v[100:103], v[16:31]
	s_waitcnt lgkmcnt(3)
	v_mfma_f32_32x32x16_f16 v[0:15], v[122:125], v[100:103], v[0:15]
	s_setprio 0
	s_setprio 1
	s_waitcnt lgkmcnt(0)
	v_mfma_f32_32x32x16_f16 v[16:31], v[36:39], v[40:43], v[16:31]
	v_mfma_f32_32x32x16_f16 v[0:15], v[32:35], v[40:43], v[0:15]
	s_setprio 0
	s_waitcnt vmcnt(0)
	s_barrier
; template <int MB, bool SWAP>
; DI void gemm_kloop(f32x16 (&acc)[MB][2], const h16* __restrict__ A, int lda, const h16* __restrict__ B, int ldb, int K, char* lds) {
;     ...
;   for (int kt = 0; kt < nk; ++kt) {
;     if (kt + 1 < nk) { if (MB == 2) asm volatile("s_waitcnt vmcnt(6)" ::: "memory"); else asm volatile("s_waitcnt vmcnt(5)" ::: "memory"); }
;     else wait_vm0();
;     __syncthreads();
;     const char* s = lds + cur * STAGE;
;     const int nbuf = cur == 0 ? 2 : cur - 1;
;     const bool more = kt + 2 < nk;
;     half8 af[2][MB], bf[2][2];
; #pragma unroll
;     for (int mb = 0; mb < MB; ++mb) af[0][mb] = *(const half8*)(s + a_rd + mb * 4096 + (((0 + hh) ^ sw) * 16));
; #pragma unroll
;     for (int nb = 0; nb < 2; ++nb) bf[0][nb] = *(const half8*)(s + b_rd + nb * 4096 + (((0 + hh) ^ sw) * 16));
; #pragma unroll
;     for (int ks = 0; ks < 4; ++ks) {
;       if (ks < 3) {
; #pragma unroll
;         for (int mb = 0; mb < MB; ++mb) af[(ks + 1) & 1][mb] = *(const half8*)(s + a_rd + mb * 4096 + (((2 * (ks + 1) + hh) ^ sw) * 16));
; #pragma unroll
;         for (int nb = 0; nb < 2; ++nb) bf[(ks + 1) & 1][nb] = *(const half8*)(s + b_rd + nb * 4096 + (((2 * (ks + 1) + hh) ^ sw) * 16));
;       }
;       if (more) {
;         if (2 * ks < NP) piece(2 * ks, kt + 2, nbuf);
;         if (2 * ks + 1 < NP) piece(2 * ks + 1, kt + 2, nbuf);
;       }
;       __builtin_amdgcn_sched_barrier(0);
;       __builtin_amdgcn_s_setprio(1);
; #pragma unroll
;       for (int mb = 0; mb < MB; ++mb)
; #pragma unroll
;         for (int nb = 0; nb < 2; ++nb)
;           acc[mb][nb] = SWAP ? __builtin_amdgcn_mfma_f32_32x32x16_f16(bf[ks & 1][nb], af[ks & 1][mb], acc[mb][nb], 0, 0, 0)
;                              : __builtin_amdgcn_mfma_f32_32x32x16_f16(af[ks & 1][mb], bf[ks & 1][nb], acc[mb][nb], 0, 0, 0);
;       __builtin_amdgcn_s_setprio(0);
;       __builtin_amdgcn_sched_barrier(0);
;     }
; template <int MB>
; DI void merge_tile(const Params& P, int layer, size_t row0, int nt, char* smem) {
;     ...
;         for (int v = 0; v < 16; ++v) gpk[mb][nb][v >> 3][v & 7] = (h16)sigmoid_f(pa2[mb][nb][v]);
;     zero_acc<MB>(pa2);
;     gemm_kloop<MB, true>(pa2, yn + row0 * LDY, LDY, wbrT + (size_t)(n * 1024 + nt * 256) * LDY, LDY, WB, smem);
; #pragma unroll
;     for (int mb = 0; mb < MB; ++mb)
; #pragma unroll
;       for (int nb = 0; nb < 2; ++nb)
; #pragma unroll
	ds_read_b128 v[32:35], v113 offset:49152
	ds_read_b128 v[36:39], v113 offset:53248
	ds_read_b128 v[40:43], v114 offset:40960
	ds_read_b128 v[100:103], v115 offset:40960
	ds_read_b128 v[118:121], v116 offset:49152
	ds_read_b128 v[114:117], v116 offset:53248
	s_setprio 1
	s_waitcnt lgkmcnt(3)
	v_mfma_f32_32x32x16_f16 v[16:31], v[32:35], v[40:43], v[16:31]
	v_mfma_f32_32x32x16_f16 v[0:15], v[36:39], v[40:43], v[0:15]
	s_setprio 0
	ds_read_b128 v[32:35], v144 offset:40960
	ds_read_b128 v[36:39], v145 offset:49152
	ds_read_b128 v[40:43], v145 offset:53248
	s_setprio 1
	s_waitcnt lgkmcnt(4)
	v_mfma_f32_32x32x16_f16 v[16:31], v[118:121], v[100:103], v[16:31]
	s_waitcnt lgkmcnt(3)
	v_mfma_f32_32x32x16_f16 v[0:15], v[114:117], v[100:103], v[0:15]
	s_setprio 0
	ds_read_b128 v[100:103], v142 offset:40960
	ds_read_b128 v[114:117], v143 offset:49152
	ds_read_b128 v[118:121], v143 offset:53248
	s_setprio 1
	s_waitcnt lgkmcnt(4)
	v_mfma_f32_32x32x16_f16 v[16:31], v[36:39], v[32:35], v[16:31]
	s_waitcnt lgkmcnt(3)
	v_mfma_f32_32x32x16_f16 v[0:15], v[40:43], v[32:35], v[0:15]
	s_setprio 0
	s_setprio 1
	s_waitcnt lgkmcnt(1)
	v_mfma_f32_32x32x16_f16 v[16:31], v[114:117], v[100:103], v[16:31]
	s_waitcnt lgkmcnt(0)
	v_mfma_f32_32x32x16_f16 v[0:15], v[118:121], v[100:103], v[0:15]
	s_setprio 0
	v_add_f32_e64 v32, v98, 1.0
	v_add_f32_e64 v33, v99, 1.0
	s_nop 6
	v_fma_mix_f32 v107, v16, v112, v107 op_sel_hi:[0,1,0]
	v_div_scale_f32 v16, s[0:1], v33, v33, 1.0
	v_rcp_f32_e32 v34, v16
	v_fma_mix_f32 v105, v0, v111, v105 op_sel_hi:[0,1,0]
	s_add_i32 s97, s97, 1
	s_add_u32 s42, s42, 0x220000
	v_fma_f32 v35, -v16, v34, 1.0
	v_fmac_f32_e32 v34, v35, v34
	v_div_scale_f32 v35, vcc, 1.0, v33, 1.0
	v_mul_f32_e32 v36, v35, v34
	v_fma_f32 v37, -v16, v36, v35
	v_fmac_f32_e32 v36, v37, v34
	v_fma_f32 v16, -v16, v36, v35
	v_div_fmas_f32 v16, v16, v34, v36
	v_div_fixup_f32 v16, v16, v33, 1.0
	v_div_scale_f32 v33, s[0:1], v32, v32, 1.0
	v_rcp_f32_e32 v34, v33
	s_addc_u32 s43, s43, 0
	v_fma_mix_f32 v106, v31, v110, v106 op_sel_hi:[0,1,0]
	v_fma_mix_f32 v104, v15, v109, v104 op_sel_hi:[0,1,0]
	v_fma_f32 v35, -v33, v34, 1.0
	v_fmac_f32_e32 v34, v35, v34
	v_div_scale_f32 v35, vcc, 1.0, v32, 1.0
	v_mul_f32_e32 v36, v35, v34
	v_fma_f32 v37, -v33, v36, v35
	v_fmac_f32_e32 v36, v37, v34
	v_fma_f32 v33, -v33, v36, v35
	v_div_fmas_f32 v33, v33, v34, v36
	v_div_fixup_f32 v32, v33, v32, 1.0
	v_cvt_pk_f16_f32 v16, v32, v16
	v_cvt_f32_f16_e32 v32, v16
	v_cvt_f32_f16_sdwa v33, v16 dst_sel:DWORD dst_unused:UNUSED_PAD src0_sel:WORD_1
	v_mov_b32_e32 v16, v17
	v_mov_b32_e32 v17, v18
	s_cmp_eq_u32 s97, 3
	v_pk_fma_f32 v[70:71], v[16:17], v[32:33], v[70:71]
	v_pk_add_f32 v[16:17], v[96:97], 1.0 op_sel_hi:[1,0]
	s_nop 0
	v_div_scale_f32 v18, s[0:1], v17, v17, 1.0
	v_rcp_f32_e32 v32, v18
	s_barrier
	v_fma_f32 v33, -v18, v32, 1.0
	v_fmac_f32_e32 v32, v33, v32
	v_div_scale_f32 v33, vcc, 1.0, v17, 1.0
	v_mul_f32_e32 v34, v33, v32
	v_fma_f32 v35, -v18, v34, v33
	v_fmac_f32_e32 v34, v35, v32
	v_fma_f32 v18, -v18, v34, v33
	v_div_fmas_f32 v18, v18, v32, v34
	v_div_fixup_f32 v17, v18, v17, 1.0
	v_div_scale_f32 v18, s[0:1], v16, v16, 1.0
	v_rcp_f32_e32 v32, v18
	s_nop 0
	v_fma_f32 v33, -v18, v32, 1.0
	v_fmac_f32_e32 v32, v33, v32
	v_div_scale_f32 v33, vcc, 1.0, v16, 1.0
	v_mul_f32_e32 v34, v33, v32
	v_fma_f32 v35, -v18, v34, v33
	v_fmac_f32_e32 v34, v35, v32
	v_fma_f32 v18, -v18, v34, v33
	v_div_fmas_f32 v18, v18, v32, v34
	v_div_fixup_f32 v16, v18, v16, 1.0
	v_cvt_pk_f16_f32 v17, v16, v17
	v_cvt_f32_f16_e32 v16, v17
	v_cvt_f32_f16_sdwa v17, v17 dst_sel:DWORD dst_unused:UNUSED_PAD src0_sel:WORD_1
	v_mov_b32_e32 v18, v19
	v_mov_b32_e32 v19, v20
	v_pk_fma_f32 v[68:69], v[18:19], v[16:17], v[68:69]
	v_pk_add_f32 v[16:17], v[94:95], 1.0 op_sel_hi:[1,0]
	s_nop 0
	v_div_scale_f32 v18, s[0:1], v17, v17, 1.0
	v_rcp_f32_e32 v19, v18
	s_nop 0
	v_fma_f32 v20, -v18, v19, 1.0
	v_fmac_f32_e32 v19, v20, v19
	v_div_scale_f32 v20, vcc, 1.0, v17, 1.0
	v_mul_f32_e32 v32, v20, v19
	v_fma_f32 v33, -v18, v32, v20
	v_fmac_f32_e32 v32, v33, v19
	v_fma_f32 v18, -v18, v32, v20
	v_div_fmas_f32 v18, v18, v19, v32
	v_div_fixup_f32 v17, v18, v17, 1.0
	v_div_scale_f32 v18, s[0:1], v16, v16, 1.0
	v_rcp_f32_e32 v19, v18
	s_nop 0
	v_fma_f32 v20, -v18, v19, 1.0
	v_fmac_f32_e32 v19, v20, v19
	v_div_scale_f32 v20, vcc, 1.0, v16, 1.0
	v_mul_f32_e32 v32, v20, v19
	v_fma_f32 v33, -v18, v32, v20
	v_fmac_f32_e32 v32, v33, v19
	v_fma_f32 v18, -v18, v32, v20
	v_div_fmas_f32 v18, v18, v19, v32
	v_div_fixup_f32 v16, v18, v16, 1.0
	v_cvt_pk_f16_f32 v17, v16, v17
	v_cvt_f32_f16_e32 v16, v17
	v_cvt_f32_f16_sdwa v17, v17 dst_sel:DWORD dst_unused:UNUSED_PAD src0_sel:WORD_1
	v_mov_b32_e32 v18, v21
	v_mov_b32_e32 v19, v22
	v_pk_fma_f32 v[66:67], v[18:19], v[16:17], v[66:67]
	v_pk_add_f32 v[16:17], v[92:93], 1.0 op_sel_hi:[1,0]
	s_nop 0
	v_div_scale_f32 v18, s[0:1], v17, v17, 1.0
	v_rcp_f32_e32 v19, v18
	s_nop 0
	v_fma_f32 v20, -v18, v19, 1.0
	v_fmac_f32_e32 v19, v20, v19
	v_div_scale_f32 v20, vcc, 1.0, v17, 1.0
	v_mul_f32_e32 v21, v20, v19
	v_fma_f32 v22, -v18, v21, v20
	v_fmac_f32_e32 v21, v22, v19
	v_fma_f32 v18, -v18, v21, v20
	v_div_fmas_f32 v18, v18, v19, v21
	v_div_fixup_f32 v17, v18, v17, 1.0
	v_div_scale_f32 v18, s[0:1], v16, v16, 1.0
	v_rcp_f32_e32 v19, v18
	s_nop 0
	v_fma_f32 v20, -v18, v19, 1.0
	v_fmac_f32_e32 v19, v20, v19
	v_div_scale_f32 v20, vcc, 1.0, v16, 1.0
	v_mul_f32_e32 v21, v20, v19
	v_fma_f32 v22, -v18, v21, v20
	v_fmac_f32_e32 v21, v22, v19
	v_fma_f32 v18, -v18, v21, v20
	v_div_fmas_f32 v18, v18, v19, v21
	v_div_fixup_f32 v16, v18, v16, 1.0
	v_cvt_pk_f16_f32 v17, v16, v17
	v_cvt_f32_f16_e32 v16, v17
; DI float sigmoid_f(float x) { return 1.f / (1.f + __expf(-x)); }
; template <int MB>
; DI void merge_tile(const Params& P, int layer, size_t row0, int nt, char* smem) {
;     ...
;         for (int v = 0; v < 16; ++v) gpk[mb][nb][v >> 3][v & 7] = (h16)sigmoid_f(pa2[mb][nb][v]);
;     zero_acc<MB>(pa2);
;     gemm_kloop<MB, true>(pa2, yn + row0 * LDY, LDY, wbrT + (size_t)(n * 1024 + nt * 256) * LDY, LDY, WB, smem);
; #pragma unroll
;     for (int mb = 0; mb < MB; ++mb)
; #pragma unroll
;       for (int nb = 0; nb < 2; ++nb)
; #pragma unroll
;         for (int v = 0; v < 16; ++v) macc[mb][nb][v] += (float)gpk[mb][nb][v >> 3][v & 7] * pa2[mb][nb][v];
	v_cvt_f32_f16_sdwa v17, v17 dst_sel:DWORD dst_unused:UNUSED_PAD src0_sel:WORD_1
	v_mov_b32_e32 v18, v23
	v_mov_b32_e32 v19, v24
	v_pk_fma_f32 v[64:65], v[18:19], v[16:17], v[64:65]
	v_pk_add_f32 v[16:17], v[90:91], 1.0 op_sel_hi:[1,0]
	s_nop 0
	v_div_scale_f32 v18, s[0:1], v17, v17, 1.0
	v_rcp_f32_e32 v19, v18
	s_nop 0
	v_fma_f32 v20, -v18, v19, 1.0
	v_fmac_f32_e32 v19, v20, v19
	v_div_scale_f32 v20, vcc, 1.0, v17, 1.0
	v_mul_f32_e32 v21, v20, v19
	v_fma_f32 v22, -v18, v21, v20
	v_fmac_f32_e32 v21, v22, v19
	v_fma_f32 v18, -v18, v21, v20
	v_div_fmas_f32 v18, v18, v19, v21
	v_div_fixup_f32 v17, v18, v17, 1.0
	v_div_scale_f32 v18, s[0:1], v16, v16, 1.0
	v_rcp_f32_e32 v19, v18
	s_nop 0
	v_fma_f32 v20, -v18, v19, 1.0
	v_fmac_f32_e32 v19, v20, v19
	v_div_scale_f32 v20, vcc, 1.0, v16, 1.0
	v_mul_f32_e32 v21, v20, v19
	v_fma_f32 v22, -v18, v21, v20
	v_fmac_f32_e32 v21, v22, v19
	v_fma_f32 v18, -v18, v21, v20
	v_div_fmas_f32 v18, v18, v19, v21
	v_div_fixup_f32 v16, v18, v16, 1.0
	v_cvt_pk_f16_f32 v17, v16, v17
	v_cvt_f32_f16_e32 v16, v17
	v_cvt_f32_f16_sdwa v17, v17 dst_sel:DWORD dst_unused:UNUSED_PAD src0_sel:WORD_1
	v_mov_b32_e32 v18, v25
	v_mov_b32_e32 v19, v26
	v_pk_fma_f32 v[62:63], v[18:19], v[16:17], v[62:63]
	v_pk_add_f32 v[16:17], v[88:89], 1.0 op_sel_hi:[1,0]
	s_nop 0
	v_div_scale_f32 v18, s[0:1], v17, v17, 1.0
	v_rcp_f32_e32 v19, v18
	s_nop 0
	v_fma_f32 v20, -v18, v19, 1.0
	v_fmac_f32_e32 v19, v20, v19
	v_div_scale_f32 v20, vcc, 1.0, v17, 1.0
	v_mul_f32_e32 v21, v20, v19
	v_fma_f32 v22, -v18, v21, v20
	v_fmac_f32_e32 v21, v22, v19
	v_fma_f32 v18, -v18, v21, v20
	v_div_fmas_f32 v18, v18, v19, v21
	v_div_fixup_f32 v17, v18, v17, 1.0
	v_div_scale_f32 v18, s[0:1], v16, v16, 1.0
	v_rcp_f32_e32 v19, v18
	s_nop 0
	v_fma_f32 v20, -v18, v19, 1.0
	v_fmac_f32_e32 v19, v20, v19
	v_div_scale_f32 v20, vcc, 1.0, v16, 1.0
	v_mul_f32_e32 v21, v20, v19
	v_fma_f32 v22, -v18, v21, v20
	v_fmac_f32_e32 v21, v22, v19
	v_fma_f32 v18, -v18, v21, v20
	v_div_fmas_f32 v18, v18, v19, v21
	v_div_fixup_f32 v16, v18, v16, 1.0
	v_cvt_pk_f16_f32 v17, v16, v17
	v_cvt_f32_f16_e32 v16, v17
	v_cvt_f32_f16_sdwa v17, v17 dst_sel:DWORD dst_unused:UNUSED_PAD src0_sel:WORD_1
	v_mov_b32_e32 v18, v27
	v_mov_b32_e32 v19, v28
	v_pk_fma_f32 v[60:61], v[18:19], v[16:17], v[60:61]
	v_pk_add_f32 v[16:17], v[86:87], 1.0 op_sel_hi:[1,0]
	s_nop 0
	v_div_scale_f32 v18, s[0:1], v17, v17, 1.0
	v_rcp_f32_e32 v19, v18
	s_nop 0
	v_fma_f32 v20, -v18, v19, 1.0
	v_fmac_f32_e32 v19, v20, v19
	v_div_scale_f32 v20, vcc, 1.0, v17, 1.0
	v_mul_f32_e32 v21, v20, v19
	v_fma_f32 v22, -v18, v21, v20
	v_fmac_f32_e32 v21, v22, v19
	v_fma_f32 v18, -v18, v21, v20
	v_div_fmas_f32 v18, v18, v19, v21
	v_div_fixup_f32 v17, v18, v17, 1.0
	v_div_scale_f32 v18, s[0:1], v16, v16, 1.0
	v_rcp_f32_e32 v19, v18
	s_nop 0
	v_fma_f32 v20, -v18, v19, 1.0
	v_fmac_f32_e32 v19, v20, v19
	v_div_scale_f32 v20, vcc, 1.0, v16, 1.0
	v_mul_f32_e32 v21, v20, v19
	v_fma_f32 v22, -v18, v21, v20
	v_fmac_f32_e32 v21, v22, v19
	v_fma_f32 v18, -v18, v21, v20
	v_div_fmas_f32 v18, v18, v19, v21
	v_div_fixup_f32 v16, v18, v16, 1.0
	v_cvt_pk_f16_f32 v17, v16, v17
	v_cvt_f32_f16_e32 v16, v17
	v_cvt_f32_f16_sdwa v17, v17 dst_sel:DWORD dst_unused:UNUSED_PAD src0_sel:WORD_1
	v_mov_b32_e32 v18, v29
	v_mov_b32_e32 v19, v30
	v_pk_fma_f32 v[58:59], v[18:19], v[16:17], v[58:59]
	v_pk_add_f32 v[16:17], v[84:85], 1.0 op_sel_hi:[1,0]
	s_nop 0
	v_div_scale_f32 v0, s[0:1], v17, v17, 1.0
	v_rcp_f32_e32 v18, v0
	s_nop 0
	v_fma_f32 v19, -v0, v18, 1.0
	v_fmac_f32_e32 v18, v19, v18
	v_div_scale_f32 v19, vcc, 1.0, v17, 1.0
	v_mul_f32_e32 v20, v19, v18
	v_fma_f32 v21, -v0, v20, v19
	v_fmac_f32_e32 v20, v21, v18
	v_fma_f32 v0, -v0, v20, v19
	v_div_fmas_f32 v0, v0, v18, v20
	v_div_fixup_f32 v0, v0, v17, 1.0
	v_div_scale_f32 v17, s[0:1], v16, v16, 1.0
	v_rcp_f32_e32 v18, v17
	s_nop 0
	v_fma_f32 v19, -v17, v18, 1.0
	v_fmac_f32_e32 v18, v19, v18
	v_div_scale_f32 v19, vcc, 1.0, v16, 1.0
	v_mul_f32_e32 v20, v19, v18
	v_fma_f32 v21, -v17, v20, v19
	v_fmac_f32_e32 v20, v21, v18
	v_fma_f32 v17, -v17, v20, v19
	v_div_fmas_f32 v17, v17, v18, v20
	v_div_fixup_f32 v16, v17, v16, 1.0
	v_cvt_pk_f16_f32 v0, v16, v0
	v_cvt_f32_f16_e32 v16, v0
	v_cvt_f32_f16_sdwa v17, v0 dst_sel:DWORD dst_unused:UNUSED_PAD src0_sel:WORD_1
	v_mov_b32_e32 v0, v1
	v_mov_b32_e32 v1, v2
	v_pk_fma_f32 v[56:57], v[0:1], v[16:17], v[56:57]
	v_pk_add_f32 v[0:1], v[82:83], 1.0 op_sel_hi:[1,0]
	s_nop 0
	v_div_scale_f32 v2, s[0:1], v1, v1, 1.0
	v_rcp_f32_e32 v16, v2
	s_nop 0
	v_fma_f32 v17, -v2, v16, 1.0
	v_fmac_f32_e32 v16, v17, v16
	v_div_scale_f32 v17, vcc, 1.0, v1, 1.0
	v_mul_f32_e32 v18, v17, v16
	v_fma_f32 v19, -v2, v18, v17
	v_fmac_f32_e32 v18, v19, v16
	v_fma_f32 v2, -v2, v18, v17
	v_div_fmas_f32 v2, v2, v16, v18
	v_div_fixup_f32 v1, v2, v1, 1.0
	v_div_scale_f32 v2, s[0:1], v0, v0, 1.0
	v_rcp_f32_e32 v16, v2
	s_nop 0
	v_fma_f32 v17, -v2, v16, 1.0
	v_fmac_f32_e32 v16, v17, v16
	v_div_scale_f32 v17, vcc, 1.0, v0, 1.0
	v_mul_f32_e32 v18, v17, v16
	v_fma_f32 v19, -v2, v18, v17
	v_fmac_f32_e32 v18, v19, v16
	v_fma_f32 v2, -v2, v18, v17
	v_div_fmas_f32 v2, v2, v16, v18
	v_div_fixup_f32 v0, v2, v0, 1.0
	v_cvt_pk_f16_f32 v1, v0, v1
; DI float sigmoid_f(float x) { return 1.f / (1.f + __expf(-x)); }
; template <int MB>
; DI void merge_tile(const Params& P, int layer, size_t row0, int nt, char* smem) {
;     ...
;         for (int v = 0; v < 16; ++v) gpk[mb][nb][v >> 3][v & 7] = (h16)sigmoid_f(pa2[mb][nb][v]);
;     zero_acc<MB>(pa2);
;     gemm_kloop<MB, true>(pa2, yn + row0 * LDY, LDY, wbrT + (size_t)(n * 1024 + nt * 256) * LDY, LDY, WB, smem);
; #pragma unroll
;     for (int mb = 0; mb < MB; ++mb)
; #pragma unroll
;       for (int nb = 0; nb < 2; ++nb)
; #pragma unroll
;         for (int v = 0; v < 16; ++v) macc[mb][nb][v] += (float)gpk[mb][nb][v >> 3][v & 7] * pa2[mb][nb][v];
;   }
	v_cvt_f32_f16_e32 v0, v1
	v_cvt_f32_f16_sdwa v1, v1 dst_sel:DWORD dst_unused:UNUSED_PAD src0_sel:WORD_1
	v_mov_b32_e32 v2, v3
	v_mov_b32_e32 v3, v4
	v_pk_fma_f32 v[54:55], v[2:3], v[0:1], v[54:55]
	v_pk_add_f32 v[0:1], v[80:81], 1.0 op_sel_hi:[1,0]
	s_nop 0
	v_div_scale_f32 v2, s[0:1], v1, v1, 1.0
	v_rcp_f32_e32 v3, v2
	s_nop 0
	v_fma_f32 v4, -v2, v3, 1.0
	v_fmac_f32_e32 v3, v4, v3
	v_div_scale_f32 v4, vcc, 1.0, v1, 1.0
	v_mul_f32_e32 v16, v4, v3
	v_fma_f32 v17, -v2, v16, v4
	v_fmac_f32_e32 v16, v17, v3
	v_fma_f32 v2, -v2, v16, v4
	v_div_fmas_f32 v2, v2, v3, v16
	v_div_fixup_f32 v1, v2, v1, 1.0
	v_div_scale_f32 v2, s[0:1], v0, v0, 1.0
	v_rcp_f32_e32 v3, v2
	s_nop 0
	v_fma_f32 v4, -v2, v3, 1.0
	v_fmac_f32_e32 v3, v4, v3
	v_div_scale_f32 v4, vcc, 1.0, v0, 1.0
	v_mul_f32_e32 v16, v4, v3
	v_fma_f32 v17, -v2, v16, v4
	v_fmac_f32_e32 v16, v17, v3
	v_fma_f32 v2, -v2, v16, v4
	v_div_fmas_f32 v2, v2, v3, v16
	v_div_fixup_f32 v0, v2, v0, 1.0
	v_cvt_pk_f16_f32 v1, v0, v1
	v_cvt_f32_f16_e32 v0, v1
	v_cvt_f32_f16_sdwa v1, v1 dst_sel:DWORD dst_unused:UNUSED_PAD src0_sel:WORD_1
	v_mov_b32_e32 v2, v5
	v_mov_b32_e32 v3, v6
	v_pk_fma_f32 v[52:53], v[2:3], v[0:1], v[52:53]
	v_pk_add_f32 v[0:1], v[78:79], 1.0 op_sel_hi:[1,0]
	s_nop 0
	v_div_scale_f32 v2, s[0:1], v1, v1, 1.0
	v_rcp_f32_e32 v3, v2
	s_nop 0
	v_fma_f32 v4, -v2, v3, 1.0
	v_fmac_f32_e32 v3, v4, v3
	v_div_scale_f32 v4, vcc, 1.0, v1, 1.0
	v_mul_f32_e32 v5, v4, v3
	v_fma_f32 v6, -v2, v5, v4
	v_fmac_f32_e32 v5, v6, v3
	v_fma_f32 v2, -v2, v5, v4
	v_div_fmas_f32 v2, v2, v3, v5
	v_div_fixup_f32 v1, v2, v1, 1.0
	v_div_scale_f32 v2, s[0:1], v0, v0, 1.0
	v_rcp_f32_e32 v3, v2
	s_nop 0
	v_fma_f32 v4, -v2, v3, 1.0
	v_fmac_f32_e32 v3, v4, v3
	v_div_scale_f32 v4, vcc, 1.0, v0, 1.0
	v_mul_f32_e32 v5, v4, v3
	v_fma_f32 v6, -v2, v5, v4
	v_fmac_f32_e32 v5, v6, v3
	v_fma_f32 v2, -v2, v5, v4
	v_div_fmas_f32 v2, v2, v3, v5
	v_div_fixup_f32 v0, v2, v0, 1.0
	v_cvt_pk_f16_f32 v1, v0, v1
	v_cvt_f32_f16_e32 v0, v1
	v_cvt_f32_f16_sdwa v1, v1 dst_sel:DWORD dst_unused:UNUSED_PAD src0_sel:WORD_1
	v_mov_b32_e32 v2, v7
	v_mov_b32_e32 v3, v8
	v_pk_fma_f32 v[50:51], v[2:3], v[0:1], v[50:51]
	v_pk_add_f32 v[0:1], v[76:77], 1.0 op_sel_hi:[1,0]
	s_nop 0
	v_div_scale_f32 v2, s[0:1], v1, v1, 1.0
	v_rcp_f32_e32 v3, v2
	s_nop 0
	v_fma_f32 v4, -v2, v3, 1.0
	v_fmac_f32_e32 v3, v4, v3
	v_div_scale_f32 v4, vcc, 1.0, v1, 1.0
	v_mul_f32_e32 v5, v4, v3
	v_fma_f32 v6, -v2, v5, v4
	v_fmac_f32_e32 v5, v6, v3
	v_fma_f32 v2, -v2, v5, v4
	v_div_fmas_f32 v2, v2, v3, v5
	v_div_fixup_f32 v1, v2, v1, 1.0
	v_div_scale_f32 v2, s[0:1], v0, v0, 1.0
	v_rcp_f32_e32 v3, v2
	s_nop 0
	v_fma_f32 v4, -v2, v3, 1.0
	v_fmac_f32_e32 v3, v4, v3
	v_div_scale_f32 v4, vcc, 1.0, v0, 1.0
	v_mul_f32_e32 v5, v4, v3
	v_fma_f32 v6, -v2, v5, v4
	v_fmac_f32_e32 v5, v6, v3
	v_fma_f32 v2, -v2, v5, v4
	v_div_fmas_f32 v2, v2, v3, v5
	v_div_fixup_f32 v0, v2, v0, 1.0
	v_cvt_pk_f16_f32 v1, v0, v1
	v_cvt_f32_f16_e32 v0, v1
	v_cvt_f32_f16_sdwa v1, v1 dst_sel:DWORD dst_unused:UNUSED_PAD src0_sel:WORD_1
	v_mov_b32_e32 v2, v9
	v_mov_b32_e32 v3, v10
	v_pk_fma_f32 v[48:49], v[2:3], v[0:1], v[48:49]
	v_pk_add_f32 v[0:1], v[74:75], 1.0 op_sel_hi:[1,0]
	s_nop 0
	v_div_scale_f32 v2, s[0:1], v1, v1, 1.0
	v_rcp_f32_e32 v3, v2
	s_nop 0
	v_fma_f32 v4, -v2, v3, 1.0
	v_fmac_f32_e32 v3, v4, v3
	v_div_scale_f32 v4, vcc, 1.0, v1, 1.0
	v_mul_f32_e32 v5, v4, v3
	v_fma_f32 v6, -v2, v5, v4
	v_fmac_f32_e32 v5, v6, v3
	v_fma_f32 v2, -v2, v5, v4
	v_div_fmas_f32 v2, v2, v3, v5
	v_div_fixup_f32 v1, v2, v1, 1.0
	v_div_scale_f32 v2, s[0:1], v0, v0, 1.0
	v_rcp_f32_e32 v3, v2
	s_nop 0
	v_fma_f32 v4, -v2, v3, 1.0
	v_fmac_f32_e32 v3, v4, v3
	v_div_scale_f32 v4, vcc, 1.0, v0, 1.0
	v_mul_f32_e32 v5, v4, v3
	v_fma_f32 v6, -v2, v5, v4
	v_fmac_f32_e32 v5, v6, v3
	v_fma_f32 v2, -v2, v5, v4
	v_div_fmas_f32 v2, v2, v3, v5
	v_div_fixup_f32 v0, v2, v0, 1.0
	v_cvt_pk_f16_f32 v1, v0, v1
	v_cvt_f32_f16_e32 v0, v1
	v_cvt_f32_f16_sdwa v1, v1 dst_sel:DWORD dst_unused:UNUSED_PAD src0_sel:WORD_1
	v_mov_b32_e32 v2, v11
	v_mov_b32_e32 v3, v12
	v_pk_fma_f32 v[46:47], v[2:3], v[0:1], v[46:47]
	v_pk_add_f32 v[0:1], v[72:73], 1.0 op_sel_hi:[1,0]
	s_nop 0
	v_div_scale_f32 v2, s[0:1], v1, v1, 1.0
	v_rcp_f32_e32 v3, v2
	s_nop 0
	v_fma_f32 v4, -v2, v3, 1.0
	v_fmac_f32_e32 v3, v4, v3
	v_div_scale_f32 v4, vcc, 1.0, v1, 1.0
	v_mul_f32_e32 v5, v4, v3
	v_fma_f32 v6, -v2, v5, v4
	v_fmac_f32_e32 v5, v6, v3
	v_fma_f32 v2, -v2, v5, v4
	v_div_fmas_f32 v2, v2, v3, v5
	v_div_fixup_f32 v1, v2, v1, 1.0
	v_div_scale_f32 v2, s[0:1], v0, v0, 1.0
	v_rcp_f32_e32 v3, v2
	s_nop 0
	v_fma_f32 v4, -v2, v3, 1.0
	v_fmac_f32_e32 v3, v4, v3
	v_div_scale_f32 v4, vcc, 1.0, v0, 1.0
	v_mul_f32_e32 v5, v4, v3
	v_fma_f32 v6, -v2, v5, v4
	v_fmac_f32_e32 v5, v6, v3
	v_fma_f32 v2, -v2, v5, v4
	v_div_fmas_f32 v2, v2, v3, v5
	v_div_fixup_f32 v0, v2, v0, 1.0
	v_cvt_pk_f16_f32 v1, v0, v1
	v_cvt_f32_f16_e32 v0, v1
	v_cvt_f32_f16_sdwa v1, v1 dst_sel:DWORD dst_unused:UNUSED_PAD src0_sel:WORD_1
	v_mov_b32_e32 v2, v13
	v_mov_b32_e32 v3, v14
	v_pk_fma_f32 v[44:45], v[2:3], v[0:1], v[44:45]
	s_cbranch_scc1 .LBB0_58
	s_mov_b64 s[44:45], 0xb28180
	s_mov_b64 vcc, 0x32e6180
	s_branch .LBB0_62

; DI void wait_vm0() { asm volatile("s_waitcnt vmcnt(0)" ::: "memory"); }
; DI int otid() { int t = threadIdx.x; asm volatile("" : "+v"(t)); return t; }
;   DI int item(int i) const { const int li = j + i * nxb; if (li >= per) return -1; const int lin = xcd * per + li; return lin < total ? lin : -1; }
; template <int MB, bool SWAP>
; DI void gemm_kloop(f32x16 (&acc)[MB][2], const h16* __restrict__ A, int lda, const h16* __restrict__ B, int ldb, int K, char* lds) {
;     ...
;   const int tid = otid(), w = tid >> 6, lane = tid & 63;
;   const int wr = w >> 2, wc = w & 3;
;   const int lrow = w * 8 + (lane >> 3), pch = lane & 7;
;   const int gch = pch ^ ((lrow >> 1) & 7);
;   const unsigned voa = (unsigned)(lrow * lda + gch * 8) * 2u, vob = (unsigned)(lrow * ldb + gch * 8) * 2u;
;   const int lofs = lrow * 128 + pch * 16;
;   const int r32 = lane & 31, hh = lane >> 5, sw = (r32 >> 1) & 7;
;   const int a_rd = (wr * 32 * MB + r32) * 128;
;   const int b_rd = A_BYTES + (wc * 64 + r32) * 128;
;   const int nk = K >> 6;
;   constexpr int NP = MB + 4;
;   auto piece = [&](int p, int kt, int buf) {
;     char* s = lds + buf * STAGE;
;     if (p < MB) __builtin_amdgcn_global_load_lds((const unsigned*)((const char*)(A + (size_t)p * 64 * lda + kt * 64) + voa), (unsigned*)(s + p * 8192 + lofs), 16, 0, 0);
;     else __builtin_amdgcn_global_load_lds((const unsigned*)((const char*)(B + (size_t)(p - MB) * 64 * ldb + kt * 64) + vob), (unsigned*)(s + A_BYTES + (p - MB) * 8192 + lofs), 16, 0, 0);
;   };
;   wait_vm0();
; #pragma unroll
;   for (int p = 0; p < NP; ++p) piece(p, 0, 0);
; #pragma unroll
;   for (int p = 0; p < NP; ++p) piece(p, 1, 1);
; DI void phase_out(const Params& P, int layer, char* smem) {
;     ...
;   for_items_xcd(nhalf, [&](int h) {
;     const int item = nfull + (h >> 1);
;     const int mt = (item >> 5) * 8 + (item & 7), nt = (item & 31) >> 3;
;     out_tile<1>(P, layer, mt * 128 + (h & 1) * 64, nt, smem);
.LBB0_748:
	s_add_i32 s2, s77, s86
	s_cmp_ge_i32 s2, s78
	s_cbranch_scc1 .LBB0_747
	v_mov_b32_e32 v6, v208
	s_ashr_i32 s3, s2, 1
	v_ashrrev_i32_e32 v7, 3, v6
	v_bfe_u32 v8, v6, 3, 3
	v_and_or_b32 v0, v7, -8, v8
	v_lshrrev_b32_e32 v1, 1, v0
	s_add_i32 s24, s3, s70
	v_xor_b32_e32 v1, v1, v6
	s_ashr_i32 s53, s24, 2
	v_lshlrev_b32_e32 v1, 3, v1
	s_and_b32 s25, s53, 0x1fffff8
	s_and_b32 s54, s3, 7
	v_mul_lo_u32 v2, v0, s6
	v_and_b32_e32 v9, 56, v1
	s_or_b32 s3, s25, s54
	s_lshl_b32 s2, s2, 6
	v_or_b32_e32 v1, v9, v2
	s_lshl_b32 s3, s3, 7
	s_and_b32 s2, s2, 64
	v_lshlrev_b32_e32 v128, 1, v1
	v_lshlrev_b32_e32 v1, 4, v6
	s_or_b32 s33, s3, s2
	v_and_b32_e32 v1, 0x70, v1
	s_and_b32 s52, s74, 64
	s_bfe_u32 s80, s24, 0x20003
	s_mul_i32 s2, s33, 0x880
	v_lshl_or_b32 v10, v0, 7, v1
	s_mul_hi_i32 s3, s33, 0x880
	s_add_u32 s2, s48, s2
	v_add_u32_e32 v42, 0, v10
	s_addc_u32 s3, s49, s3
	s_mul_i32 s55, s80, 0x88000
	v_readfirstlane_b32 s56, v42
	s_add_u32 s24, s75, s55
	s_waitcnt vmcnt(0)
	s_mov_b32 m0, s56
	v_add_u32_e32 v4, 0x2000, v42
	s_addc_u32 s25, s76, 0
	v_lshl_add_u64 v[2:3], s[2:3], 0, v[128:129]
	global_load_lds_dwordx4 v128, s[2:3]
	v_readfirstlane_b32 s2, v4
	v_lshl_add_u64 v[0:1], s[24:25], 0, v[128:129]
	s_mov_b32 m0, s2
	s_mov_b64 s[2:3], 0x22000
	v_add_u32_e32 v11, 0x4000, v42
	v_lshl_add_u64 v[4:5], v[0:1], 0, s[2:3]
	v_readfirstlane_b32 s2, v11
	global_load_lds_dwordx4 v128, s[24:25]
	s_mov_b32 m0, s2
	s_mov_b64 s[2:3], 0x44000
	v_add_u32_e32 v11, 0x6000, v42
	global_load_lds_dwordx4 v[4:5], off
	v_lshl_add_u64 v[4:5], v[0:1], 0, s[2:3]
	v_readfirstlane_b32 s2, v11
	s_mov_b32 m0, s2
	s_mov_b64 s[2:3], 0x66000
	v_add_u32_e32 v11, 0x8000, v42
	global_load_lds_dwordx4 v[4:5], off
	v_lshl_add_u64 v[4:5], v[0:1], 0, s[2:3]
	v_readfirstlane_b32 s2, v11
	s_mov_b32 m0, s2
	v_lshl_add_u64 v[2:3], v[2:3], 0, s[22:23]
	global_load_lds_dwordx4 v[4:5], off
	v_add_u32_e32 v4, 0xa000, v42
	v_readlane_b32 s36, v253, 1
	v_readfirstlane_b32 s2, v4
	v_add_u32_e32 v4, 0xc000, v42
	s_mov_b32 m0, s2
	v_readfirstlane_b32 s2, v4
	global_load_lds_dwordx4 v[2:3], off
	v_lshl_add_u64 v[2:3], v[0:1], 0, s[22:23]
	s_mov_b32 m0, s2
	s_mov_b64 s[2:3], 0x22080
	v_add_u32_e32 v4, 0xe000, v42
	global_load_lds_dwordx4 v[2:3], off
	v_lshl_add_u64 v[2:3], v[0:1], 0, s[2:3]
	v_readfirstlane_b32 s2, v4
	s_mov_b32 m0, s2
	s_mov_b64 s[2:3], 0x44080
	v_add_u32_e32 v4, s8, v10
	global_load_lds_dwordx4 v[2:3], off
	v_lshl_add_u64 v[2:3], v[0:1], 0, s[2:3]
	v_readfirstlane_b32 s2, v4
	s_mov_b32 m0, s2
	s_mov_b64 s[2:3], 0x66080
	global_load_lds_dwordx4 v[2:3], off
	v_add_u32_e32 v2, s9, v10
	v_lshl_add_u64 v[0:1], v[0:1], 0, s[2:3]
	v_readfirstlane_b32 s2, v2
	s_mov_b32 m0, s2
	v_lshlrev_b32_e32 v2, 7, v6
	global_load_lds_dwordx4 v[0:1], off
	v_and_b32_e32 v0, 31, v6
	v_lshrrev_b32_e32 v1, 1, v6
	v_and_or_b32 v0, v7, s16, v0
	v_and_b32_e32 v39, 0x6f80, v2
	v_bfe_u32 v2, v6, 5, 1
	v_lshlrev_b32_e32 v41, 7, v0
	v_bfe_u32 v0, v6, 1, 3
	v_bitop3_b32 v1, v2, v1, 7 bitop3:0x78
	v_lshlrev_b32_e32 v40, 4, v1
	v_bitop3_b32 v1, v2, v0, 2 bitop3:0x36
	s_lshl_b32 s2, s53, 7
	v_lshlrev_b32_e32 v38, 4, v1
	v_bitop3_b32 v1, v2, v0, 4 bitop3:0x36
	v_bitop3_b32 v0, v2, v0, 6 bitop3:0x36
	s_and_b32 s2, s2, 0xfffffc00
	s_lshl_b32 s3, s54, 7
	v_lshlrev_b32_e32 v36, 4, v0
	s_or_b32 s2, s2, s3
	v_lshrrev_b32_e32 v0, 3, v7
	s_or_b32 s2, s2, s52
	v_mul_lo_u32 v0, v0, s11
	s_mul_hi_i32 s3, s2, 0x880
	s_mulk_i32 s2, 0x880
	v_mad_u32_u24 v0, v8, s6, v0
	v_readlane_b32 s50, v253, 15
	v_or_b32_e32 v0, v0, v9
	v_readlane_b32 s51, v253, 16
	s_add_u32 s2, s50, s2
	v_lshlrev_b32_e32 v128, 1, v0
	s_addc_u32 s3, s51, s3
	v_lshl_add_u64 v[32:33], s[2:3], 0, v[128:129]
	s_add_u32 s2, s57, s55
	v_readlane_b32 s37, v253, 2
	v_readlane_b32 s38, v253, 3
	v_readlane_b32 s39, v253, 4
	s_addc_u32 s3, s62, 0
	v_mov_b32_e32 v16, 0
	v_lshlrev_b32_e32 v37, 4, v1
	v_lshl_add_u64 v[34:35], s[2:3], 0, v[128:129]
	s_mov_b32 s24, 0
	s_mov_b64 s[2:3], 0
	v_mov_b32_e32 v17, v16
	v_mov_b32_e32 v18, v16
	v_mov_b32_e32 v19, v16
	v_mov_b32_e32 v20, v16
	v_mov_b32_e32 v21, v16
	v_mov_b32_e32 v22, v16
	v_mov_b32_e32 v23, v16
	v_mov_b32_e32 v24, v16
	v_mov_b32_e32 v25, v16
	v_mov_b32_e32 v26, v16
	v_mov_b32_e32 v27, v16
	v_mov_b32_e32 v28, v16
	v_mov_b32_e32 v29, v16
	v_mov_b32_e32 v30, v16
	v_mov_b32_e32 v31, v16
	v_mov_b32_e32 v0, v16
	v_mov_b32_e32 v1, v16
	v_mov_b32_e32 v2, v16
	v_mov_b32_e32 v3, v16
	v_mov_b32_e32 v4, v16
	v_mov_b32_e32 v5, v16
	v_mov_b32_e32 v6, v16
	v_mov_b32_e32 v7, v16
	v_mov_b32_e32 v8, v16
	v_mov_b32_e32 v9, v16
	v_mov_b32_e32 v10, v16
	v_mov_b32_e32 v11, v16
	v_mov_b32_e32 v12, v16
	v_mov_b32_e32 v13, v16
	v_mov_b32_e32 v14, v16
	v_mov_b32_e32 v15, v16
	s_mov_b64 s[36:37], 0x152c100
	s_mov_b64 s[38:39], 0x154e180
	v_readlane_b32 s40, v253, 5
	v_readlane_b32 s41, v253, 6
	v_readlane_b32 s42, v253, 7
	v_readlane_b32 s43, v253, 8
	v_readlane_b32 s44, v253, 9
	v_readlane_b32 s45, v253, 10
	v_readlane_b32 s46, v253, 11
	v_readlane_b32 s47, v253, 12
	v_readlane_b32 s48, v253, 13
	v_readlane_b32 s49, v253, 14
	v_readfirstlane_b32 s25, v208
	s_nop 0
	s_lshr_b32 s25, s25, 8
	s_cmp_lg_u32 s25, 0
	s_cbranch_scc1 .Lst1_750_top
; DI void wait_vm0() { asm volatile("s_waitcnt vmcnt(0)" ::: "memory"); }
; template <int MB, bool SWAP>
; DI void gemm_kloop(f32x16 (&acc)[MB][2], const h16* __restrict__ A, int lda, const h16* __restrict__ B, int ldb, int K, char* lds) {
;     ...
;   for (int kt = 0; kt < nk; ++kt) {
;     if (kt + 1 < nk) { if (MB == 2) asm volatile("s_waitcnt vmcnt(6)" ::: "memory"); else asm volatile("s_waitcnt vmcnt(5)" ::: "memory"); }
;     else wait_vm0();
;     __syncthreads();
;     const char* s = lds + cur * STAGE;
;     const int nbuf = cur == 0 ? 2 : cur - 1;
;     const bool more = kt + 2 < nk;
;     half8 af[2][MB], bf[2][2];
; #pragma unroll
;     for (int mb = 0; mb < MB; ++mb) af[0][mb] = *(const half8*)(s + a_rd + mb * 4096 + (((0 + hh) ^ sw) * 16));
; #pragma unroll
;     for (int nb = 0; nb < 2; ++nb) bf[0][nb] = *(const half8*)(s + b_rd + nb * 4096 + (((0 + hh) ^ sw) * 16));
; #pragma unroll
;     for (int ks = 0; ks < 4; ++ks) {
;       if (ks < 3) {
; #pragma unroll
;         for (int mb = 0; mb < MB; ++mb) af[(ks + 1) & 1][mb] = *(const half8*)(s + a_rd + mb * 4096 + (((2 * (ks + 1) + hh) ^ sw) * 16));
; #pragma unroll
;         for (int nb = 0; nb < 2; ++nb) bf[(ks + 1) & 1][nb] = *(const half8*)(s + b_rd + nb * 4096 + (((2 * (ks + 1) + hh) ^ sw) * 16));
;       }
;       if (more) {
;         if (2 * ks < NP) piece(2 * ks, kt + 2, nbuf);
;         if (2 * ks + 1 < NP) piece(2 * ks + 1, kt + 2, nbuf);
;       }
;       __builtin_amdgcn_sched_barrier(0);
;       __builtin_amdgcn_s_setprio(1);
; #pragma unroll
;       for (int mb = 0; mb < MB; ++mb)
; #pragma unroll
;         for (int nb = 0; nb < 2; ++nb)
;           acc[mb][nb] = SWAP ? __builtin_amdgcn_mfma_f32_32x32x16_f16(bf[ks & 1][nb], af[ks & 1][mb], acc[mb][nb], 0, 0, 0)
;                              : __builtin_amdgcn_mfma_f32_32x32x16_f16(af[ks & 1][mb], bf[ks & 1][nb], acc[mb][nb], 0, 0, 0);
;       __builtin_amdgcn_s_setprio(0);
;       __builtin_amdgcn_sched_barrier(0);
;     }
;     cur = cur == 2 ? 0 : cur + 1;
;   }
.LBB0_750:
	s_mul_i32 s25, s24, 0xa000
	s_add_i32 s52, s25, 0
	s_add_i32 s25, s25, 0xffff6000
	s_cmp_lg_u32 s24, 0
	s_cselect_b32 s25, s25, 0x14000
	v_add_u32_e32 v77, s25, v42
	v_add_u32_e32 v43, s52, v41
	v_add_u32_e32 v76, s52, v39
	v_add_u32_e32 v78, 0x2000, v77
	v_lshl_add_u64 v[72:73], v[32:33], 0, s[2:3]
	v_readfirstlane_b32 s25, v77
	v_add_u32_e32 v48, v76, v40
	v_lshl_add_u64 v[68:69], v[34:35], 0, s[2:3]
	v_add_u32_e32 v52, v43, v40
	v_add_u32_e32 v56, v43, v38
	v_add_u32_e32 v64, v76, v38
	v_lshl_add_u64 v[74:75], v[72:73], 0, s[12:13]
	s_mov_b32 m0, s25
	v_readfirstlane_b32 s25, v78
	s_waitcnt vmcnt(5)
	s_waitcnt lgkmcnt(0)
	s_barrier
	ds_read_b128 v[44:47], v48 offset:8192
	ds_read_b128 v[48:51], v48 offset:12288
	v_lshl_add_u64 v[70:71], v[68:69], 0, s[4:5]
	ds_read_b128 v[52:55], v52
	ds_read_b128 v[56:59], v56
	ds_read_b128 v[60:63], v64 offset:8192
	ds_read_b128 v[64:67], v64 offset:12288
	global_load_lds_dwordx4 v[74:75], off
	s_mov_b32 m0, s25
	s_nop 0
	global_load_lds_dwordx4 v[70:71], off
	s_setprio 1
	s_waitcnt lgkmcnt(0)
	v_mfma_f32_32x32x16_f16 v[16:31], v[44:47], v[52:55], v[16:31]
	v_mfma_f32_32x32x16_f16 v[0:15], v[48:51], v[52:55], v[0:15]
	s_setprio 0
	v_add_u32_e32 v79, 0x4000, v77
	v_add_u32_e32 v78, 0x6000, v77
	v_readfirstlane_b32 s25, v79
	v_add_u32_e32 v44, v43, v37
	v_add_u32_e32 v52, v76, v37
	v_lshl_add_u64 v[74:75], v[68:69], 0, s[14:15]
	s_mov_b32 m0, s25
	v_readfirstlane_b32 s25, v78
	ds_read_b128 v[44:47], v44
	ds_read_b128 v[48:51], v52 offset:8192
	ds_read_b128 v[52:55], v52 offset:12288
	v_lshl_add_u64 v[70:71], v[68:69], 0, s[36:37]
	global_load_lds_dwordx4 v[74:75], off
	s_mov_b32 m0, s25
	s_nop 0
	global_load_lds_dwordx4 v[70:71], off
	s_setprio 1
	v_mfma_f32_32x32x16_f16 v[16:31], v[60:63], v[56:59], v[16:31]
	v_mfma_f32_32x32x16_f16 v[0:15], v[64:67], v[56:59], v[0:15]
	s_setprio 0
	v_add_u32_e32 v43, v43, v36
	v_add_u32_e32 v64, v76, v36
	ds_read_b128 v[56:59], v43
	ds_read_b128 v[60:63], v64 offset:8192
	ds_read_b128 v[64:67], v64 offset:12288
	v_add_u32_e32 v43, 0x8000, v77
	v_lshl_add_u64 v[70:71], v[68:69], 0, s[18:19]
	v_readfirstlane_b32 s25, v43
	s_mov_b32 m0, s25
	s_nop 0
	global_load_lds_dwordx4 v[70:71], off
	s_setprio 1
	s_waitcnt lgkmcnt(0)
	v_mfma_f32_32x32x16_f16 v[16:31], v[48:51], v[44:47], v[16:31]
	v_mfma_f32_32x32x16_f16 v[0:15], v[52:55], v[44:47], v[0:15]
	s_setprio 0
	s_setprio 1
	v_mfma_f32_32x32x16_f16 v[16:31], v[60:63], v[56:59], v[16:31]
	v_mfma_f32_32x32x16_f16 v[0:15], v[64:67], v[56:59], v[0:15]
	s_setprio 0
	s_add_i32 s25, s24, 1
	s_cmp_lg_u32 s24, 2
	s_cselect_b32 s24, s25, 0
	s_mul_i32 s25, s24, 0xa000
	s_add_i32 s52, s25, 0
	s_add_i32 s25, s25, 0xffff6000
	s_cmp_lg_u32 s24, 0
	s_cselect_b32 s25, s25, 0x14000
	v_add_u32_e32 v75, s25, v42
	v_add_u32_e32 v43, s52, v41
	v_add_u32_e32 v74, s52, v39
	v_add_u32_e32 v76, 0x2000, v75
	v_readfirstlane_b32 s25, v75
	v_add_u32_e32 v48, v74, v40
	v_add_u32_e32 v52, v43, v40
	v_add_u32_e32 v56, v43, v38
	v_add_u32_e32 v64, v74, v38
	v_lshl_add_u64 v[72:73], v[72:73], 0, s[66:67]
	s_mov_b32 m0, s25
	v_readfirstlane_b32 s25, v76
	s_waitcnt vmcnt(5)
	s_waitcnt lgkmcnt(0)
	s_barrier
	ds_read_b128 v[44:47], v48 offset:8192
	ds_read_b128 v[48:51], v48 offset:12288
	v_lshl_add_u64 v[70:71], v[68:69], 0, s[64:65]
	ds_read_b128 v[52:55], v52
	ds_read_b128 v[56:59], v56
	ds_read_b128 v[60:63], v64 offset:8192
	ds_read_b128 v[64:67], v64 offset:12288
	global_load_lds_dwordx4 v[72:73], off
	s_mov_b32 m0, s25
	s_nop 0
	global_load_lds_dwordx4 v[70:71], off
	s_setprio 1
	s_waitcnt lgkmcnt(0)
	v_mfma_f32_32x32x16_f16 v[16:31], v[44:47], v[52:55], v[16:31]
	v_mfma_f32_32x32x16_f16 v[0:15], v[48:51], v[52:55], v[0:15]
	s_setprio 0
	v_add_u32_e32 v77, 0x4000, v75
	v_add_u32_e32 v76, 0x6000, v75
	v_readfirstlane_b32 s25, v77
	v_add_u32_e32 v44, v43, v37
	v_add_u32_e32 v52, v74, v37
	v_lshl_add_u64 v[72:73], v[68:69], 0, vcc
	s_mov_b32 m0, s25
	v_readfirstlane_b32 s25, v76
	ds_read_b128 v[44:47], v44
	ds_read_b128 v[48:51], v52 offset:8192
	ds_read_b128 v[52:55], v52 offset:12288
	v_lshl_add_u64 v[70:71], v[68:69], 0, s[96:97]
	global_load_lds_dwordx4 v[72:73], off
	s_mov_b32 m0, s25
	s_nop 0
	global_load_lds_dwordx4 v[70:71], off
	s_setprio 1
	v_mfma_f32_32x32x16_f16 v[16:31], v[60:63], v[56:59], v[16:31]
	v_mfma_f32_32x32x16_f16 v[0:15], v[64:67], v[56:59], v[0:15]
	s_setprio 0
	v_add_u32_e32 v43, v43, v36
	v_add_u32_e32 v64, v74, v36
	ds_read_b128 v[56:59], v43
	ds_read_b128 v[60:63], v64 offset:8192
	ds_read_b128 v[64:67], v64 offset:12288
	v_add_u32_e32 v43, 0x8000, v75
	v_lshl_add_u64 v[68:69], v[68:69], 0, s[38:39]
	v_readfirstlane_b32 s25, v43
	s_mov_b32 m0, s25
	s_nop 0
	global_load_lds_dwordx4 v[68:69], off
	s_setprio 1
	s_waitcnt lgkmcnt(0)
	v_mfma_f32_32x32x16_f16 v[16:31], v[48:51], v[44:47], v[16:31]
	v_mfma_f32_32x32x16_f16 v[0:15], v[52:55], v[44:47], v[0:15]
	s_setprio 0
	s_setprio 1
	v_mfma_f32_32x32x16_f16 v[16:31], v[60:63], v[56:59], v[16:31]
	v_mfma_f32_32x32x16_f16 v[0:15], v[64:67], v[56:59], v[0:15]
	s_setprio 0
	s_add_i32 s25, s24, 1
	s_cmp_lg_u32 s24, 2
	s_cselect_b32 s24, s25, 0
	s_add_u32 s2, s2, 0x100
	s_addc_u32 s3, s3, 0
	s_cmpk_eq_i32 s2, 0x700
	s_cbranch_scc0 .LBB0_750
	s_branch .Lst1_750_join
; DI void wait_vm0() { asm volatile("s_waitcnt vmcnt(0)" ::: "memory"); }
; template <int MB, bool SWAP>
; DI void gemm_kloop(f32x16 (&acc)[MB][2], const h16* __restrict__ A, int lda, const h16* __restrict__ B, int ldb, int K, char* lds) {
;     ...
;   for (int kt = 0; kt < nk; ++kt) {
;     if (kt + 1 < nk) { if (MB == 2) asm volatile("s_waitcnt vmcnt(6)" ::: "memory"); else asm volatile("s_waitcnt vmcnt(5)" ::: "memory"); }
;     else wait_vm0();
;     __syncthreads();
;     const char* s = lds + cur * STAGE;
;     const int nbuf = cur == 0 ? 2 : cur - 1;
;     const bool more = kt + 2 < nk;
;     half8 af[2][MB], bf[2][2];
; #pragma unroll
;     for (int mb = 0; mb < MB; ++mb) af[0][mb] = *(const half8*)(s + a_rd + mb * 4096 + (((0 + hh) ^ sw) * 16));
; #pragma unroll
;     for (int nb = 0; nb < 2; ++nb) bf[0][nb] = *(const half8*)(s + b_rd + nb * 4096 + (((0 + hh) ^ sw) * 16));
; #pragma unroll
;     for (int ks = 0; ks < 4; ++ks) {
;       if (ks < 3) {
; #pragma unroll
;         for (int mb = 0; mb < MB; ++mb) af[(ks + 1) & 1][mb] = *(const half8*)(s + a_rd + mb * 4096 + (((2 * (ks + 1) + hh) ^ sw) * 16));
; #pragma unroll
;         for (int nb = 0; nb < 2; ++nb) bf[(ks + 1) & 1][nb] = *(const half8*)(s + b_rd + nb * 4096 + (((2 * (ks + 1) + hh) ^ sw) * 16));
;       }
;       if (more) {
;         if (2 * ks < NP) piece(2 * ks, kt + 2, nbuf);
;         if (2 * ks + 1 < NP) piece(2 * ks + 1, kt + 2, nbuf);
;       }
;       __builtin_amdgcn_sched_barrier(0);
;       __builtin_amdgcn_s_setprio(1);
; #pragma unroll
;       for (int mb = 0; mb < MB; ++mb)
; #pragma unroll
;         for (int nb = 0; nb < 2; ++nb)
;           acc[mb][nb] = SWAP ? __builtin_amdgcn_mfma_f32_32x32x16_f16(bf[ks & 1][nb], af[ks & 1][mb], acc[mb][nb], 0, 0, 0)
;                              : __builtin_amdgcn_mfma_f32_32x32x16_f16(af[ks & 1][mb], bf[ks & 1][nb], acc[mb][nb], 0, 0, 0);
;       __builtin_amdgcn_s_setprio(0);
;       __builtin_amdgcn_sched_barrier(0);
;     }
;     cur = cur == 2 ? 0 : cur + 1;
;   }
.Lst1_750_top:
	s_mul_i32 s25, s24, 0xa000
	s_add_i32 s52, s25, 0
	s_add_i32 s25, s25, 0xffff6000
	s_cmp_lg_u32 s24, 0
	s_cselect_b32 s25, s25, 0x14000
	v_add_u32_e32 v77, s25, v42
	v_add_u32_e32 v43, s52, v41
	v_add_u32_e32 v76, s52, v39
	v_add_u32_e32 v78, 0x2000, v77
	v_lshl_add_u64 v[72:73], v[32:33], 0, s[2:3]
	v_readfirstlane_b32 s25, v77
	v_lshl_add_u64 v[68:69], v[34:35], 0, s[2:3]
	v_lshl_add_u64 v[74:75], v[72:73], 0, s[12:13]
	s_mov_b32 m0, s25
	v_readfirstlane_b32 s25, v78
	s_waitcnt vmcnt(5)
	s_waitcnt lgkmcnt(0)
	s_barrier
	s_cmp_eq_u32 s2, 0
	s_cbranch_scc1 .Lst1_750_skip
	s_setprio 1
	v_mfma_f32_32x32x16_f16 v[16:31], v[48:51], v[44:47], v[16:31]
	v_mfma_f32_32x32x16_f16 v[0:15], v[52:55], v[44:47], v[0:15]
	v_mfma_f32_32x32x16_f16 v[16:31], v[60:63], v[56:59], v[16:31]
	v_mfma_f32_32x32x16_f16 v[0:15], v[64:67], v[56:59], v[0:15]
	s_setprio 0
.Lst1_750_skip:
	v_add_u32_e32 v48, v76, v40
	v_add_u32_e32 v52, v43, v40
	v_add_u32_e32 v56, v43, v38
	v_add_u32_e32 v64, v76, v38
	ds_read_b128 v[44:47], v48 offset:8192
	ds_read_b128 v[48:51], v48 offset:12288
	v_lshl_add_u64 v[70:71], v[68:69], 0, s[4:5]
	ds_read_b128 v[52:55], v52
	ds_read_b128 v[56:59], v56
	ds_read_b128 v[60:63], v64 offset:8192
	ds_read_b128 v[64:67], v64 offset:12288
	global_load_lds_dwordx4 v[74:75], off
	s_mov_b32 m0, s25
	s_nop 0
	global_load_lds_dwordx4 v[70:71], off
	s_setprio 1
	s_waitcnt lgkmcnt(0)
	v_mfma_f32_32x32x16_f16 v[16:31], v[44:47], v[52:55], v[16:31]
	v_mfma_f32_32x32x16_f16 v[0:15], v[48:51], v[52:55], v[0:15]
	s_setprio 0
	v_add_u32_e32 v79, 0x4000, v77
	v_add_u32_e32 v78, 0x6000, v77
	v_readfirstlane_b32 s25, v79
	v_add_u32_e32 v44, v43, v37
	v_add_u32_e32 v52, v76, v37
	v_lshl_add_u64 v[74:75], v[68:69], 0, s[14:15]
	s_mov_b32 m0, s25
	v_readfirstlane_b32 s25, v78
	ds_read_b128 v[44:47], v44
	ds_read_b128 v[48:51], v52 offset:8192
	ds_read_b128 v[52:55], v52 offset:12288
	v_lshl_add_u64 v[70:71], v[68:69], 0, s[36:37]
	global_load_lds_dwordx4 v[74:75], off
	s_mov_b32 m0, s25
	s_nop 0
	global_load_lds_dwordx4 v[70:71], off
	s_setprio 1
	v_mfma_f32_32x32x16_f16 v[16:31], v[60:63], v[56:59], v[16:31]
	v_mfma_f32_32x32x16_f16 v[0:15], v[64:67], v[56:59], v[0:15]
	s_setprio 0
	v_add_u32_e32 v43, v43, v36
	v_add_u32_e32 v64, v76, v36
	ds_read_b128 v[56:59], v43
	ds_read_b128 v[60:63], v64 offset:8192
	ds_read_b128 v[64:67], v64 offset:12288
	v_add_u32_e32 v43, 0x8000, v77
	v_lshl_add_u64 v[70:71], v[68:69], 0, s[18:19]
	v_readfirstlane_b32 s25, v43
	s_mov_b32 m0, s25
	s_nop 0
	global_load_lds_dwordx4 v[70:71], off
	s_add_i32 s25, s24, 1
	s_cmp_lg_u32 s24, 2
	s_cselect_b32 s24, s25, 0
	s_mul_i32 s25, s24, 0xa000
	s_add_i32 s52, s25, 0
	s_add_i32 s25, s25, 0xffff6000
	s_cmp_lg_u32 s24, 0
	s_cselect_b32 s25, s25, 0x14000
	v_add_u32_e32 v75, s25, v42
	v_add_u32_e32 v43, s52, v41
	v_add_u32_e32 v74, s52, v39
	v_add_u32_e32 v76, 0x2000, v75
	v_readfirstlane_b32 s25, v75
	v_lshl_add_u64 v[72:73], v[72:73], 0, s[66:67]
	s_mov_b32 m0, s25
	v_readfirstlane_b32 s25, v76
	s_waitcnt vmcnt(5)
	s_waitcnt lgkmcnt(0)
	s_barrier
	s_setprio 1
	v_mfma_f32_32x32x16_f16 v[16:31], v[48:51], v[44:47], v[16:31]
	v_mfma_f32_32x32x16_f16 v[0:15], v[52:55], v[44:47], v[0:15]
	v_mfma_f32_32x32x16_f16 v[16:31], v[60:63], v[56:59], v[16:31]
	v_mfma_f32_32x32x16_f16 v[0:15], v[64:67], v[56:59], v[0:15]
	s_setprio 0
	v_add_u32_e32 v48, v74, v40
	v_add_u32_e32 v52, v43, v40
	v_add_u32_e32 v56, v43, v38
	v_add_u32_e32 v64, v74, v38
	ds_read_b128 v[44:47], v48 offset:8192
	ds_read_b128 v[48:51], v48 offset:12288
	v_lshl_add_u64 v[70:71], v[68:69], 0, s[64:65]
	ds_read_b128 v[52:55], v52
	ds_read_b128 v[56:59], v56
	ds_read_b128 v[60:63], v64 offset:8192
	ds_read_b128 v[64:67], v64 offset:12288
	global_load_lds_dwordx4 v[72:73], off
	s_mov_b32 m0, s25
	s_nop 0
	global_load_lds_dwordx4 v[70:71], off
	s_setprio 1
	s_waitcnt lgkmcnt(0)
	v_mfma_f32_32x32x16_f16 v[16:31], v[44:47], v[52:55], v[16:31]
	v_mfma_f32_32x32x16_f16 v[0:15], v[48:51], v[52:55], v[0:15]
	s_setprio 0
	v_add_u32_e32 v77, 0x4000, v75
	v_add_u32_e32 v76, 0x6000, v75
	v_readfirstlane_b32 s25, v77
	v_add_u32_e32 v44, v43, v37
	v_add_u32_e32 v52, v74, v37
	v_lshl_add_u64 v[72:73], v[68:69], 0, vcc
	s_mov_b32 m0, s25
	v_readfirstlane_b32 s25, v76
	ds_read_b128 v[44:47], v44
	ds_read_b128 v[48:51], v52 offset:8192
	ds_read_b128 v[52:55], v52 offset:12288
	v_lshl_add_u64 v[70:71], v[68:69], 0, s[96:97]
	global_load_lds_dwordx4 v[72:73], off
	s_mov_b32 m0, s25
	s_nop 0
	global_load_lds_dwordx4 v[70:71], off
	s_setprio 1
	v_mfma_f32_32x32x16_f16 v[16:31], v[60:63], v[56:59], v[16:31]
	v_mfma_f32_32x32x16_f16 v[0:15], v[64:67], v[56:59], v[0:15]
	s_setprio 0
	v_add_u32_e32 v43, v43, v36
	v_add_u32_e32 v64, v74, v36
	ds_read_b128 v[56:59], v43
	ds_read_b128 v[60:63], v64 offset:8192
	ds_read_b128 v[64:67], v64 offset:12288
	v_add_u32_e32 v43, 0x8000, v75
	v_lshl_add_u64 v[68:69], v[68:69], 0, s[38:39]
	v_readfirstlane_b32 s25, v43
	s_mov_b32 m0, s25
	s_nop 0
	global_load_lds_dwordx4 v[68:69], off
	s_add_i32 s25, s24, 1
	s_cmp_lg_u32 s24, 2
	s_cselect_b32 s24, s25, 0
	s_add_u32 s2, s2, 0x100
	s_addc_u32 s3, s3, 0
	s_cmpk_eq_i32 s2, 0x700
	s_cbranch_scc0 .Lst1_750_top
	s_waitcnt lgkmcnt(0)
	s_setprio 1
	v_mfma_f32_32x32x16_f16 v[16:31], v[48:51], v[44:47], v[16:31]
	v_mfma_f32_32x32x16_f16 v[0:15], v[52:55], v[44:47], v[0:15]
	v_mfma_f32_32x32x16_f16 v[16:31], v[60:63], v[56:59], v[16:31]
	v_mfma_f32_32x32x16_f16 v[0:15], v[64:67], v[56:59], v[0:15]
	s_setprio 0
; template <int MB, bool SWAP>
; DI void gemm_kloop(f32x16 (&acc)[MB][2], const h16* __restrict__ A, int lda, const h16* __restrict__ B, int ldb, int K, char* lds) {
;     ...
;   for (int kt = 0; kt < nk; ++kt) {
;     if (kt + 1 < nk) { if (MB == 2) asm volatile("s_waitcnt vmcnt(6)" ::: "memory"); else asm volatile("s_waitcnt vmcnt(5)" ::: "memory"); }
;     else wait_vm0();
;     __syncthreads();
;     const char* s = lds + cur * STAGE;
;     const int nbuf = cur == 0 ? 2 : cur - 1;
;     const bool more = kt + 2 < nk;
;     half8 af[2][MB], bf[2][2];
; #pragma unroll
;     for (int mb = 0; mb < MB; ++mb) af[0][mb] = *(const half8*)(s + a_rd + mb * 4096 + (((0 + hh) ^ sw) * 16));
; #pragma unroll
;     for (int nb = 0; nb < 2; ++nb) bf[0][nb] = *(const half8*)(s + b_rd + nb * 4096 + (((0 + hh) ^ sw) * 16));
; #pragma unroll
;     for (int ks = 0; ks < 4; ++ks) {
;       if (ks < 3) {
; #pragma unroll
;         for (int mb = 0; mb < MB; ++mb) af[(ks + 1) & 1][mb] = *(const half8*)(s + a_rd + mb * 4096 + (((2 * (ks + 1) + hh) ^ sw) * 16));
; #pragma unroll
;         for (int nb = 0; nb < 2; ++nb) bf[(ks + 1) & 1][nb] = *(const half8*)(s + b_rd + nb * 4096 + (((2 * (ks + 1) + hh) ^ sw) * 16));
;       }
;       if (more) {
;         if (2 * ks < NP) piece(2 * ks, kt + 2, nbuf);
;         if (2 * ks + 1 < NP) piece(2 * ks + 1, kt + 2, nbuf);
;       }
;       __builtin_amdgcn_sched_barrier(0);
;       __builtin_amdgcn_s_setprio(1);
; #pragma unroll
;       for (int mb = 0; mb < MB; ++mb)
; #pragma unroll
;         for (int nb = 0; nb < 2; ++nb)
;           acc[mb][nb] = SWAP ? __builtin_amdgcn_mfma_f32_32x32x16_f16(bf[ks & 1][nb], af[ks & 1][mb], acc[mb][nb], 0, 0, 0)
;                              : __builtin_amdgcn_mfma_f32_32x32x16_f16(af[ks & 1][mb], bf[ks & 1][nb], acc[mb][nb], 0, 0, 0);
;       __builtin_amdgcn_s_setprio(0);
;       __builtin_amdgcn_sched_barrier(0);
;     }
;     cur = cur == 2 ? 0 : cur + 1;
;   }
;   __syncthreads();
; template <int MB>
; DI void out_tile(const Params& P, int layer, int row0, int nt, char* smem) {
;     ...
;   const int tid = otid(), lane = tid & 63, w = tid >> 6, wr = w >> 2, wc = w & 3, r32 = lane & 31, hh = lane >> 5;
; #pragma unroll
;   for (int mb = 0; mb < MB; ++mb) {
;     const int row = row0 + wr * 32 * MB + mb * 32 + r32;
;     const float* src; float* dst; int b;
.Lst1_750_join:
	v_add_u32_e32 v62, s79, v41
	v_add3_u32 v42, s79, v40, v39
	v_add_u32_e32 v46, v62, v40
	v_add_u32_e32 v50, v62, v38
	v_add3_u32 v58, s79, v38, v39
	s_waitcnt vmcnt(5)
	s_waitcnt lgkmcnt(0)
	s_barrier
	ds_read_b128 v[32:35], v42 offset:8192
	ds_read_b128 v[42:45], v42 offset:12288
	ds_read_b128 v[46:49], v46
	ds_read_b128 v[50:53], v50
	ds_read_b128 v[54:57], v58 offset:8192
	ds_read_b128 v[58:61], v58 offset:12288
	s_setprio 1
	s_waitcnt lgkmcnt(3)
	v_mfma_f32_32x32x16_f16 v[16:31], v[32:35], v[46:49], v[16:31]
	v_mfma_f32_32x32x16_f16 v[0:15], v[42:45], v[46:49], v[0:15]
	s_setprio 0
	v_add_u32_e32 v32, v62, v37
	v_add3_u32 v46, s79, v37, v39
	ds_read_b128 v[32:35], v32
	ds_read_b128 v[42:45], v46 offset:8192
	ds_read_b128 v[46:49], v46 offset:12288
	s_setprio 1
	s_waitcnt lgkmcnt(4)
	v_mfma_f32_32x32x16_f16 v[16:31], v[54:57], v[50:53], v[16:31]
	s_waitcnt lgkmcnt(3)
	v_mfma_f32_32x32x16_f16 v[0:15], v[58:61], v[50:53], v[0:15]
	s_setprio 0
	v_add_u32_e32 v50, v62, v36
	v_add3_u32 v58, s79, v36, v39
	ds_read_b128 v[50:53], v50
	ds_read_b128 v[54:57], v58 offset:8192
	ds_read_b128 v[58:61], v58 offset:12288
	s_setprio 1
	s_waitcnt lgkmcnt(4)
	v_mfma_f32_32x32x16_f16 v[16:31], v[42:45], v[32:35], v[16:31]
	s_waitcnt lgkmcnt(3)
	v_mfma_f32_32x32x16_f16 v[0:15], v[46:49], v[32:35], v[0:15]
	s_setprio 0
	s_setprio 1
	s_waitcnt lgkmcnt(1)
	v_mfma_f32_32x32x16_f16 v[16:31], v[54:57], v[50:53], v[16:31]
	s_waitcnt lgkmcnt(0)
	v_mfma_f32_32x32x16_f16 v[0:15], v[58:61], v[50:53], v[0:15]
	s_setprio 0
	v_add_u32_e32 v59, 0, v39
	v_add_u32_e32 v58, 0, v41
	v_add_u32_e32 v39, v59, v40
	s_waitcnt vmcnt(0)
	s_barrier
	ds_read_b128 v[32:35], v39 offset:8192
	ds_read_b128 v[42:45], v39 offset:12288
	v_add_u32_e32 v39, v58, v40
	v_add_u32_e32 v40, v58, v38
	v_add_u32_e32 v54, v59, v38
	ds_read_b128 v[46:49], v39
	ds_read_b128 v[50:53], v40
	ds_read_b128 v[38:41], v54 offset:8192
	ds_read_b128 v[54:57], v54 offset:12288
	s_setprio 1
	s_waitcnt lgkmcnt(3)
	v_mfma_f32_32x32x16_f16 v[16:31], v[32:35], v[46:49], v[16:31]
	v_mfma_f32_32x32x16_f16 v[0:15], v[42:45], v[46:49], v[0:15]
	s_setprio 0
	v_add_u32_e32 v32, v58, v37
	v_add_u32_e32 v37, v59, v37
	ds_read_b128 v[32:35], v32
	ds_read_b128 v[42:45], v37 offset:8192
	ds_read_b128 v[46:49], v37 offset:12288
	s_setprio 1
	s_waitcnt lgkmcnt(4)
	v_mfma_f32_32x32x16_f16 v[16:31], v[38:41], v[50:53], v[16:31]
	s_waitcnt lgkmcnt(3)
	v_mfma_f32_32x32x16_f16 v[0:15], v[54:57], v[50:53], v[0:15]
	s_setprio 0
	v_add_u32_e32 v37, v58, v36
	v_add_u32_e32 v40, v59, v36
	ds_read_b128 v[36:39], v37
	ds_read_b128 v[50:53], v40 offset:8192
	ds_read_b128 v[54:57], v40 offset:12288
	s_setprio 1
	s_waitcnt lgkmcnt(4)
	v_mfma_f32_32x32x16_f16 v[16:31], v[42:45], v[32:35], v[16:31]
	s_waitcnt lgkmcnt(3)
	v_mfma_f32_32x32x16_f16 v[0:15], v[46:49], v[32:35], v[0:15]
	s_setprio 0
	s_setprio 1
	s_waitcnt lgkmcnt(1)
	v_mfma_f32_32x32x16_f16 v[16:31], v[50:53], v[36:39], v[16:31]
	s_waitcnt lgkmcnt(0)
	v_mfma_f32_32x32x16_f16 v[0:15], v[54:57], v[36:39], v[0:15]
	s_setprio 0
	v_mov_b32_e32 v40, v208
	s_barrier
	s_movk_i32 s2, 0x7fff
	v_ashrrev_i32_e32 v32, 3, v40
	v_and_b32_e32 v32, 0xffffffe0, v32
	v_and_or_b32 v33, v40, 31, s33
	v_add_u32_e32 v36, v33, v32
	v_cmp_lt_i32_e32 vcc, s2, v36
	s_and_saveexec_b64 s[2:3], vcc
	s_xor_b64 s[2:3], exec, s[2:3]
	s_cbranch_execz .LBB0_753
	v_add_u32_e32 v128, 0xffff8000, v36
	v_readlane_b32 s36, v253, 1
	v_lshlrev_b64 v[32:33], 12, v[128:129]
	v_readlane_b32 s50, v253, 15
	v_readlane_b32 s51, v253, 16
	v_readlane_b32 s37, v253, 2
	v_readlane_b32 s38, v253, 3
	v_readlane_b32 s39, v253, 4
	v_readlane_b32 s40, v253, 5
	v_readlane_b32 s41, v253, 6
	v_readlane_b32 s42, v253, 7
	v_readlane_b32 s43, v253, 8
	v_readlane_b32 s44, v253, 9
	v_readlane_b32 s45, v253, 10
	v_readlane_b32 s46, v253, 11
	v_readlane_b32 s47, v253, 12
	v_readlane_b32 s48, v253, 13
	v_readlane_b32 s49, v253, 14
	v_lshl_add_u64 v[38:39], s[50:51], 0, v[32:33]
	v_lshl_add_u64 v[32:33], s[0:1], 0, v[32:33]
